# next layer's RMSNorm+adaLN fused into the out-proj epilogue: x_out stays in the accumulator registers across the grid barrier, per-row partial sums of squares via the dead modp scratch; norm phase of
# speedup vs baseline: 1.0119x; 1.0065x over previous
.LBB0_57:
	s_cmp_gt_i32 s68, 0
	s_waitcnt vmcnt(6)
	s_cselect_b32 s69, -1, 2
	s_mul_i32 s70, s68, 0x6000
	s_waitcnt lgkmcnt(0)
	s_add_i32 s69, s69, s68
	v_add_u32_e32 v135, s70, v149
	v_add_u32_e32 v0, s70, v148
	s_mulk_i32 s69, 0x6000
	v_add_u32_e32 v164, v135, v152
	s_barrier
	v_lshl_add_u64 v[180:181], v[138:139], 0, s[0:1]
	v_add_u32_e32 v159, s69, v146
	v_lshl_add_u64 v[184:185], v[136:137], 0, s[0:1]
	v_add_u32_e32 v192, s69, v147
	v_add_u32_e32 v176, v0, v152
	ds_read_b128 v[140:143], v176
	ds_read_b128 v[160:163], v164
	ds_read_b128 v[164:167], v164 offset:2048
	v_lshl_add_u64 v[182:183], v[180:181], 0, s[88:89]
	v_lshl_add_u64 v[186:187], v[184:185], 0, s[88:89]
	v_add_u32_e32 v193, 0x4000, v192
	v_lshl_add_u64 v[188:189], v[180:181], 0, s[90:91]
	v_add_u32_e32 v194, 0x400, v159
	v_lshl_add_u64 v[190:191], v[180:181], 0, s[78:79]
	v_add_u32_e32 v195, 0x800, v159
	ds_read_b128 v[168:171], v176 offset:2048
	ds_read_b128 v[172:175], v176 offset:4096
	ds_read_b128 v[176:179], v176 offset:6144
	s_waitcnt lgkmcnt(3)
	s_setprio 1
	v_mfma_f32_32x32x16_bf16 v[114:129], v[140:143], v[160:163], v[114:129]
	v_mfma_f32_32x32x16_bf16 v[98:113], v[140:143], v[164:167], v[98:113]
	v_readfirstlane_b32 s69, v159
	s_mov_b32 m0, s69
	s_nop 0
	global_load_lds_dwordx4 v[182:183], off
	s_waitcnt lgkmcnt(2)
	v_mfma_f32_32x32x16_bf16 v[82:97], v[168:171], v[160:163], v[82:97]
	v_mfma_f32_32x32x16_bf16 v[66:81], v[168:171], v[164:167], v[66:81]
	v_readfirstlane_b32 s69, v194
	s_mov_b32 m0, s69
	s_nop 0
	global_load_lds_dwordx4 v[188:189], off
	s_waitcnt lgkmcnt(1)
	v_mfma_f32_32x32x16_bf16 v[50:65], v[172:175], v[160:163], v[50:65]
	v_mfma_f32_32x32x16_bf16 v[34:49], v[172:175], v[164:167], v[34:49]
	v_readfirstlane_b32 s69, v195
	s_mov_b32 m0, s69
	s_nop 0
	global_load_lds_dwordx4 v[190:191], off
	s_waitcnt lgkmcnt(0)
	v_mfma_f32_32x32x16_bf16 v[18:33], v[176:179], v[160:163], v[18:33]
	v_mfma_f32_32x32x16_bf16 v[2:17], v[176:179], v[164:167], v[2:17]
	s_setprio 0
	v_add_u32_e32 v0, v0, v153
	v_add_u32_e32 v135, v135, v153
	ds_read_b128 v[140:143], v0
	ds_read_b128 v[160:163], v135
	ds_read_b128 v[164:167], v135 offset:2048
	ds_read_b128 v[168:171], v0 offset:2048
	ds_read_b128 v[172:175], v0 offset:4096
	ds_read_b128 v[176:179], v0 offset:6144
	s_waitcnt lgkmcnt(3)
	s_setprio 1
	v_mfma_f32_32x32x16_bf16 v[114:129], v[140:143], v[160:163], v[114:129]
	v_mfma_f32_32x32x16_bf16 v[98:113], v[140:143], v[164:167], v[98:113]
	v_add_u32_e32 v0, 0xc00, v159
	v_lshl_add_u64 v[140:141], v[180:181], 0, s[76:77]
	v_readfirstlane_b32 s69, v0
	s_mov_b32 m0, s69
	s_nop 0
	global_load_lds_dwordx4 v[140:141], off
	s_waitcnt lgkmcnt(2)
	v_mfma_f32_32x32x16_bf16 v[82:97], v[168:171], v[160:163], v[82:97]
	v_mfma_f32_32x32x16_bf16 v[66:81], v[168:171], v[164:167], v[66:81]
	v_readfirstlane_b32 s69, v193
	s_mov_b32 m0, s69
	s_nop 0
	global_load_lds_dwordx4 v[186:187], off
	s_waitcnt lgkmcnt(1)
	v_mfma_f32_32x32x16_bf16 v[50:65], v[172:175], v[160:163], v[50:65]
	v_mfma_f32_32x32x16_bf16 v[34:49], v[172:175], v[164:167], v[34:49]
	v_add_u32_e32 v0, 0x4400, v192
	v_lshl_add_u64 v[140:141], v[184:185], 0, s[90:91]
	v_readfirstlane_b32 s69, v0
	s_mov_b32 m0, s69
	s_nop 0
	global_load_lds_dwordx4 v[140:141], off
	s_waitcnt lgkmcnt(0)
	v_mfma_f32_32x32x16_bf16 v[18:33], v[176:179], v[160:163], v[18:33]
	v_mfma_f32_32x32x16_bf16 v[2:17], v[176:179], v[164:167], v[2:17]
	s_setprio 0
	s_add_i32 s69, s68, 1
	s_cmp_lt_i32 s68, 2
	s_cselect_b32 s68, s69, 0
	s_add_u32 s0, s0, 0x80
	s_addc_u32 s1, s1, 0
	s_cmpk_eq_i32 s0, 0xf00
	s_cbranch_scc0 .LBB0_57
	s_waitcnt vmcnt(6)
	s_mul_i32 s0, s68, 0x6000
	s_waitcnt lgkmcnt(0)
	v_add_u32_e32 v135, s0, v149
	v_add_u32_e32 v0, s0, v148
	v_add_u32_e32 v160, v135, v152
	s_barrier
	v_add_u32_e32 v159, v0, v152
	ds_read_b128 v[136:139], v159
	ds_read_b128 v[140:143], v160
	ds_read_b128 v[160:163], v160 offset:2048
	ds_read_b128 v[164:167], v159 offset:2048
	ds_read_b128 v[168:171], v159 offset:4096
	ds_read_b128 v[172:175], v159 offset:6144
	s_waitcnt lgkmcnt(3)
	s_setprio 1
	v_mfma_f32_32x32x16_bf16 v[114:129], v[136:139], v[140:143], v[114:129]
	v_mfma_f32_32x32x16_bf16 v[98:113], v[136:139], v[160:163], v[98:113]
	s_waitcnt lgkmcnt(2)
	v_mfma_f32_32x32x16_bf16 v[82:97], v[164:167], v[140:143], v[82:97]
	v_mfma_f32_32x32x16_bf16 v[66:81], v[164:167], v[160:163], v[66:81]
	s_waitcnt lgkmcnt(1)
	v_mfma_f32_32x32x16_bf16 v[50:65], v[168:171], v[140:143], v[50:65]
	v_mfma_f32_32x32x16_bf16 v[34:49], v[168:171], v[160:163], v[34:49]
	s_waitcnt lgkmcnt(0)
	v_mfma_f32_32x32x16_bf16 v[18:33], v[172:175], v[140:143], v[18:33]
	v_mfma_f32_32x32x16_bf16 v[2:17], v[172:175], v[160:163], v[2:17]
	s_setprio 0
	v_add_u32_e32 v0, v0, v153
	v_add_u32_e32 v135, v135, v153
	ds_read_b128 v[136:139], v0
	ds_read_b128 v[140:143], v135
	ds_read_b128 v[160:163], v135 offset:2048
	ds_read_b128 v[164:167], v0 offset:2048
	ds_read_b128 v[168:171], v0 offset:4096
	ds_read_b128 v[172:175], v0 offset:6144
	s_waitcnt lgkmcnt(3)
	s_setprio 1
	v_mfma_f32_32x32x16_bf16 v[114:129], v[136:139], v[140:143], v[114:129]
	v_mfma_f32_32x32x16_bf16 v[98:113], v[136:139], v[160:163], v[98:113]
	s_waitcnt lgkmcnt(2)
	v_mfma_f32_32x32x16_bf16 v[82:97], v[164:167], v[140:143], v[82:97]
	v_mfma_f32_32x32x16_bf16 v[66:81], v[164:167], v[160:163], v[66:81]
	s_waitcnt lgkmcnt(1)
	v_mfma_f32_32x32x16_bf16 v[50:65], v[168:171], v[140:143], v[50:65]
	v_mfma_f32_32x32x16_bf16 v[34:49], v[168:171], v[160:163], v[34:49]
	s_waitcnt lgkmcnt(0)
	v_mfma_f32_32x32x16_bf16 v[18:33], v[172:175], v[140:143], v[18:33]
	v_mfma_f32_32x32x16_bf16 v[2:17], v[172:175], v[160:163], v[2:17]
	s_setprio 0
	s_waitcnt vmcnt(0)
	s_waitcnt lgkmcnt(0)
	s_barrier
	ds_read_b128 v[136:139], v154
	ds_read_b128 v[140:143], v155
	ds_read_b128 v[160:163], v155 offset:2048
	ds_read_b128 v[164:167], v154 offset:2048
	ds_read_b128 v[168:171], v154 offset:4096
	ds_read_b128 v[172:175], v154 offset:6144
	s_waitcnt lgkmcnt(3)
	s_setprio 1
	v_mfma_f32_32x32x16_bf16 v[114:129], v[136:139], v[140:143], v[114:129]
	v_mfma_f32_32x32x16_bf16 v[98:113], v[136:139], v[160:163], v[98:113]
	s_waitcnt lgkmcnt(2)
	v_mfma_f32_32x32x16_bf16 v[82:97], v[164:167], v[140:143], v[82:97]
	v_mfma_f32_32x32x16_bf16 v[66:81], v[164:167], v[160:163], v[66:81]
	s_waitcnt lgkmcnt(1)
	v_mfma_f32_32x32x16_bf16 v[50:65], v[168:171], v[140:143], v[50:65]
	v_mfma_f32_32x32x16_bf16 v[34:49], v[168:171], v[160:163], v[34:49]
	s_waitcnt lgkmcnt(0)
	v_mfma_f32_32x32x16_bf16 v[18:33], v[172:175], v[140:143], v[18:33]
	v_mfma_f32_32x32x16_bf16 v[2:17], v[172:175], v[160:163], v[2:17]
	s_setprio 0
	ds_read_b128 v[136:139], v156
	ds_read_b128 v[140:143], v157
	ds_read_b128 v[160:163], v157 offset:2048
	ds_read_b128 v[164:167], v156 offset:2048
	ds_read_b128 v[168:171], v156 offset:4096
	ds_read_b128 v[172:175], v156 offset:6144
	s_waitcnt lgkmcnt(3)
	s_setprio 1
	v_mfma_f32_32x32x16_bf16 v[114:129], v[136:139], v[140:143], v[114:129]
	v_mfma_f32_32x32x16_bf16 v[98:113], v[136:139], v[160:163], v[98:113]
	s_waitcnt lgkmcnt(2)
	v_mfma_f32_32x32x16_bf16 v[82:97], v[164:167], v[140:143], v[82:97]
	v_mfma_f32_32x32x16_bf16 v[66:81], v[164:167], v[160:163], v[66:81]
	s_waitcnt lgkmcnt(1)
	v_mfma_f32_32x32x16_bf16 v[50:65], v[168:171], v[140:143], v[50:65]
	v_mfma_f32_32x32x16_bf16 v[34:49], v[168:171], v[160:163], v[34:49]
	s_waitcnt lgkmcnt(0)
	v_mfma_f32_32x32x16_bf16 v[18:33], v[172:175], v[140:143], v[18:33]
	v_mfma_f32_32x32x16_bf16 v[2:17], v[172:175], v[160:163], v[2:17]
	s_setprio 0
	v_add_u32_e32 v138, s29, v151
	v_or_b32_e32 v136, s31, v150
	v_ashrrev_i32_e32 v139, 31, v138
	v_lshlrev_b64 v[142:143], 10, v[138:139]
	v_ashrrev_i32_e32 v137, 31, v136
	v_lshl_add_u64 v[142:143], v[142:143], 0, v[136:137]
	s_ashr_i32 s0, s28, 4
	v_lshlrev_b64 v[160:161], 2, v[142:143]
	s_add_i32 s0, s0, s10
	v_lshl_add_u64 v[142:143], s[98:99], 0, v[160:161]
	s_movk_i32 s29, 0x2000
	s_mul_hi_i32 s1, s0, 0x3000
	s_mulk_i32 s0, 0x3000
	v_add_co_u32_e32 v162, vcc, s29, v142
	s_add_u32 s0, s4, s0
	s_nop 0
	v_addc_co_u32_e32 v163, vcc, 0, v143, vcc
	s_addc_u32 s1, s5, s1
	v_add_co_u32_e32 v164, vcc, s73, v142
	s_add_u32 s0, s0, 0x2000
	s_nop 0
	v_addc_co_u32_e32 v165, vcc, 0, v143, vcc
	s_addc_u32 s1, s1, 0
	v_add_co_u32_e32 v166, vcc, s75, v142
	v_lshl_add_u64 v[140:141], v[136:137], 2, s[0:1]
	s_nop 0
	v_addc_co_u32_e32 v167, vcc, 0, v143, vcc
	s_waitcnt vmcnt(0) lgkmcnt(0)
	s_barrier
	v_and_b32_e32 v195, 63, v200
	v_lshrrev_b32_e32 v193, 5, v195
	v_and_b32_e32 v130, 31, v195
	v_lshlrev_b32_e32 v131, 2, v193
	v_sub_u32_e32 v138, v138, v131
	v_sub_u32_e32 v136, v136, v130
	v_lshrrev_b32_e32 v131, 6, v200
	v_mul_u32_u24_e32 v131, 0x2200, v131
	v_lshlrev_b32_e32 v130, 2, v130
	s_movk_i32 s28, 0x440
	v_mad_u32_u24 v130, v193, s28, v130
	v_add_u32_e32 v130, v130, v131
	v_lshrrev_b32_e32 v193, 4, v195
	v_and_b32_e32 v192, 15, v195
	s_movk_i32 s28, 0x110
	v_mad_u32_u24 v131, v193, s28, v131
	v_lshl_add_u32 v131, v192, 4, v131
	v_lshrrev_b32_e32 v194, 6, v136
	v_add_u32_e32 v138, v138, v193
	v_lshl_add_u32 v194, v194, 14, v138
	v_lshlrev_b32_e32 v194, 2, v194
	v_lshl_add_u32 v136, v192, 2, v136
	v_lshlrev_b32_e32 v195, 2, v136
	global_load_dwordx4 v[180:183], v195, s[0:1]
	v_lshl_add_u32 v0, v138, 10, v136
	v_lshlrev_b32_e32 v0, 2, v0
	s_mov_b64 s[36:37], s[98:99]
	s_mov_b64 s[38:39], s[56:57]
	v_readlane_b32 s28, v243, 5
	v_readlane_b32 s29, v243, 6
	global_load_dwordx4 v[148:151], v0, s[36:37] nt
	s_add_u32 s36, s36, 0x4000
	s_addc_u32 s37, s37, 0
	global_load_dwordx4 v[152:155], v0, s[36:37] nt
	s_add_u32 s36, s36, 0x4000
	s_addc_u32 s37, s37, 0
	global_load_dwordx4 v[156:159], v0, s[36:37] nt
	s_add_u32 s36, s36, 0x4000
	s_addc_u32 s37, s37, 0
	global_load_dwordx4 v[160:163], v0, s[36:37] nt
	s_add_u32 s36, s36, 0x4000
	s_addc_u32 s37, s37, 0
	global_load_dwordx4 v[164:167], v0, s[36:37] nt
	s_add_u32 s36, s36, 0x4000
	s_addc_u32 s37, s37, 0
	global_load_dwordx4 v[168:171], v0, s[36:37] nt
	s_add_u32 s36, s36, 0x4000
	s_addc_u32 s37, s37, 0
	global_load_dwordx4 v[172:175], v0, s[36:37] nt
	s_add_u32 s36, s36, 0x4000
	s_addc_u32 s37, s37, 0
	global_load_dwordx4 v[176:179], v0, s[36:37] nt
	s_add_u32 s36, s36, 0x4000
	s_addc_u32 s37, s37, 0
	ds_write2_b32 v130, v114, v98 offset0:0 offset1:32
	ds_write2_b32 v130, v115, v99 offset0:68 offset1:100
	ds_write2_b32 v130, v116, v100 offset0:136 offset1:168
	ds_write2_b32 v130, v117, v101 offset0:204 offset1:236
	v_add_u32_e32 v130, 0x880, v130
	ds_write2_b32 v130, v118, v102 offset0:0 offset1:32
	ds_write2_b32 v130, v119, v103 offset0:68 offset1:100
	ds_write2_b32 v130, v120, v104 offset0:136 offset1:168
	ds_write2_b32 v130, v121, v105 offset0:204 offset1:236
	v_add_u32_e32 v130, 0x880, v130
	ds_write2_b32 v130, v122, v106 offset0:0 offset1:32
	ds_write2_b32 v130, v123, v107 offset0:68 offset1:100
	ds_write2_b32 v130, v124, v108 offset0:136 offset1:168
	ds_write2_b32 v130, v125, v109 offset0:204 offset1:236
	v_add_u32_e32 v130, 0x880, v130
	ds_write2_b32 v130, v126, v110 offset0:0 offset1:32
	ds_write2_b32 v130, v127, v111 offset0:68 offset1:100
	ds_write2_b32 v130, v128, v112 offset0:136 offset1:168
	ds_write2_b32 v130, v129, v113 offset0:204 offset1:236
	v_subrev_u32_e32 v130, 0x1980, v130
	s_waitcnt lgkmcnt(0)
	ds_read_b128 v[98:101], v131
	ds_read_b128 v[102:105], v131 offset:1088
	ds_read_b128 v[106:109], v131 offset:2176
	ds_read_b128 v[110:113], v131 offset:3264
	ds_read_b128 v[114:117], v131 offset:4352
	ds_read_b128 v[118:121], v131 offset:5440
	ds_read_b128 v[122:125], v131 offset:6528
	ds_read_b128 v[126:129], v131 offset:7616
	s_waitcnt vmcnt(0) lgkmcnt(0)
	v_fma_f32 v98, v98, v180, v148
	v_fma_f32 v99, v99, v181, v149
	v_fma_f32 v100, v100, v182, v150
	v_fma_f32 v101, v101, v183, v151
	global_store_dwordx4 v0, v[98:101], s[38:39] nt
	s_add_u32 s38, s38, 0x4000
	s_addc_u32 s39, s39, 0
	v_mul_f32_e32 v184, v98, v98
	v_fmac_f32_e32 v184, v99, v99
	v_fmac_f32_e32 v184, v100, v100
	v_fmac_f32_e32 v184, v101, v101
	v_fma_f32 v102, v102, v180, v152
	v_fma_f32 v103, v103, v181, v153
	v_fma_f32 v104, v104, v182, v154
	v_fma_f32 v105, v105, v183, v155
	global_store_dwordx4 v0, v[102:105], s[38:39] nt
	s_add_u32 s38, s38, 0x4000
	s_addc_u32 s39, s39, 0
	v_mul_f32_e32 v185, v102, v102
	v_fmac_f32_e32 v185, v103, v103
	v_fmac_f32_e32 v185, v104, v104
	v_fmac_f32_e32 v185, v105, v105
	v_fma_f32 v106, v106, v180, v156
	v_fma_f32 v107, v107, v181, v157
	v_fma_f32 v108, v108, v182, v158
	v_fma_f32 v109, v109, v183, v159
	global_store_dwordx4 v0, v[106:109], s[38:39] nt
	s_add_u32 s38, s38, 0x4000
	s_addc_u32 s39, s39, 0
	v_mul_f32_e32 v186, v106, v106
	v_fmac_f32_e32 v186, v107, v107
	v_fmac_f32_e32 v186, v108, v108
	v_fmac_f32_e32 v186, v109, v109
	v_fma_f32 v110, v110, v180, v160
	v_fma_f32 v111, v111, v181, v161
	v_fma_f32 v112, v112, v182, v162
	v_fma_f32 v113, v113, v183, v163
	global_store_dwordx4 v0, v[110:113], s[38:39] nt
	s_add_u32 s38, s38, 0x4000
	s_addc_u32 s39, s39, 0
	v_mul_f32_e32 v187, v110, v110
	v_fmac_f32_e32 v187, v111, v111
	v_fmac_f32_e32 v187, v112, v112
	v_fmac_f32_e32 v187, v113, v113
	v_fma_f32 v114, v114, v180, v164
	v_fma_f32 v115, v115, v181, v165
	v_fma_f32 v116, v116, v182, v166
	v_fma_f32 v117, v117, v183, v167
	global_store_dwordx4 v0, v[114:117], s[38:39] nt
	s_add_u32 s38, s38, 0x4000
	s_addc_u32 s39, s39, 0
	v_mul_f32_e32 v188, v114, v114
	v_fmac_f32_e32 v188, v115, v115
	v_fmac_f32_e32 v188, v116, v116
	v_fmac_f32_e32 v188, v117, v117
	v_fma_f32 v118, v118, v180, v168
	v_fma_f32 v119, v119, v181, v169
	v_fma_f32 v120, v120, v182, v170
	v_fma_f32 v121, v121, v183, v171
	global_store_dwordx4 v0, v[118:121], s[38:39] nt
	s_add_u32 s38, s38, 0x4000
	s_addc_u32 s39, s39, 0
	v_mul_f32_e32 v189, v118, v118
	v_fmac_f32_e32 v189, v119, v119
	v_fmac_f32_e32 v189, v120, v120
	v_fmac_f32_e32 v189, v121, v121
	v_fma_f32 v122, v122, v180, v172
	v_fma_f32 v123, v123, v181, v173
	v_fma_f32 v124, v124, v182, v174
	v_fma_f32 v125, v125, v183, v175
	global_store_dwordx4 v0, v[122:125], s[38:39] nt
	s_add_u32 s38, s38, 0x4000
	s_addc_u32 s39, s39, 0
	v_mul_f32_e32 v190, v122, v122
	v_fmac_f32_e32 v190, v123, v123
	v_fmac_f32_e32 v190, v124, v124
	v_fmac_f32_e32 v190, v125, v125
	v_fma_f32 v126, v126, v180, v176
	v_fma_f32 v127, v127, v181, v177
	v_fma_f32 v128, v128, v182, v178
	v_fma_f32 v129, v129, v183, v179
	global_store_dwordx4 v0, v[126:129], s[38:39] nt
	s_add_u32 s38, s38, 0x4000
	s_addc_u32 s39, s39, 0
	v_mul_f32_e32 v191, v126, v126
	v_fmac_f32_e32 v191, v127, v127
	v_fmac_f32_e32 v191, v128, v128
	v_fmac_f32_e32 v191, v129, v129
	global_load_dwordx4 v[148:151], v0, s[36:37] nt
	s_add_u32 s36, s36, 0x4000
	s_addc_u32 s37, s37, 0
	global_load_dwordx4 v[152:155], v0, s[36:37] nt
	s_add_u32 s36, s36, 0x4000
	s_addc_u32 s37, s37, 0
	global_load_dwordx4 v[156:159], v0, s[36:37] nt
	s_add_u32 s36, s36, 0x4000
	s_addc_u32 s37, s37, 0
	global_load_dwordx4 v[160:163], v0, s[36:37] nt
	s_add_u32 s36, s36, 0x4000
	s_addc_u32 s37, s37, 0
	global_load_dwordx4 v[164:167], v0, s[36:37] nt
	s_add_u32 s36, s36, 0x4000
	s_addc_u32 s37, s37, 0
	global_load_dwordx4 v[168:171], v0, s[36:37] nt
	s_add_u32 s36, s36, 0x4000
	s_addc_u32 s37, s37, 0
	global_load_dwordx4 v[172:175], v0, s[36:37] nt
	s_add_u32 s36, s36, 0x4000
	s_addc_u32 s37, s37, 0
	global_load_dwordx4 v[176:179], v0, s[36:37] nt
	s_add_u32 s36, s36, 0x4000
	s_addc_u32 s37, s37, 0
	v_add_f32_dpp v184, v184, v184 quad_perm:[1,0,3,2] row_mask:0xf bank_mask:0xf
	v_add_f32_dpp v185, v185, v185 quad_perm:[1,0,3,2] row_mask:0xf bank_mask:0xf
	v_add_f32_dpp v186, v186, v186 quad_perm:[1,0,3,2] row_mask:0xf bank_mask:0xf
	v_add_f32_dpp v187, v187, v187 quad_perm:[1,0,3,2] row_mask:0xf bank_mask:0xf
	v_add_f32_dpp v188, v188, v188 quad_perm:[1,0,3,2] row_mask:0xf bank_mask:0xf
	v_add_f32_dpp v189, v189, v189 quad_perm:[1,0,3,2] row_mask:0xf bank_mask:0xf
	v_add_f32_dpp v190, v190, v190 quad_perm:[1,0,3,2] row_mask:0xf bank_mask:0xf
	v_add_f32_dpp v191, v191, v191 quad_perm:[1,0,3,2] row_mask:0xf bank_mask:0xf
	v_add_f32_dpp v184, v184, v184 quad_perm:[2,3,0,1] row_mask:0xf bank_mask:0xf
	v_add_f32_dpp v185, v185, v185 quad_perm:[2,3,0,1] row_mask:0xf bank_mask:0xf
	v_add_f32_dpp v186, v186, v186 quad_perm:[2,3,0,1] row_mask:0xf bank_mask:0xf
	v_add_f32_dpp v187, v187, v187 quad_perm:[2,3,0,1] row_mask:0xf bank_mask:0xf
	v_add_f32_dpp v188, v188, v188 quad_perm:[2,3,0,1] row_mask:0xf bank_mask:0xf
	v_add_f32_dpp v189, v189, v189 quad_perm:[2,3,0,1] row_mask:0xf bank_mask:0xf
	v_add_f32_dpp v190, v190, v190 quad_perm:[2,3,0,1] row_mask:0xf bank_mask:0xf
	v_add_f32_dpp v191, v191, v191 quad_perm:[2,3,0,1] row_mask:0xf bank_mask:0xf
	v_add_f32_dpp v184, v184, v184 row_half_mirror row_mask:0xf bank_mask:0xf
	v_add_f32_dpp v185, v185, v185 row_half_mirror row_mask:0xf bank_mask:0xf
	v_add_f32_dpp v186, v186, v186 row_half_mirror row_mask:0xf bank_mask:0xf
	v_add_f32_dpp v187, v187, v187 row_half_mirror row_mask:0xf bank_mask:0xf
	v_add_f32_dpp v188, v188, v188 row_half_mirror row_mask:0xf bank_mask:0xf
	v_add_f32_dpp v189, v189, v189 row_half_mirror row_mask:0xf bank_mask:0xf
	v_add_f32_dpp v190, v190, v190 row_half_mirror row_mask:0xf bank_mask:0xf
	v_add_f32_dpp v191, v191, v191 row_half_mirror row_mask:0xf bank_mask:0xf
	v_add_f32_dpp v184, v184, v184 row_mirror row_mask:0xf bank_mask:0xf
	v_add_f32_dpp v185, v185, v185 row_mirror row_mask:0xf bank_mask:0xf
	v_add_f32_dpp v186, v186, v186 row_mirror row_mask:0xf bank_mask:0xf
	v_add_f32_dpp v187, v187, v187 row_mirror row_mask:0xf bank_mask:0xf
	v_add_f32_dpp v188, v188, v188 row_mirror row_mask:0xf bank_mask:0xf
	v_add_f32_dpp v189, v189, v189 row_mirror row_mask:0xf bank_mask:0xf
	v_add_f32_dpp v190, v190, v190 row_mirror row_mask:0xf bank_mask:0xf
	v_add_f32_dpp v191, v191, v191 row_mirror row_mask:0xf bank_mask:0xf
	v_cmp_eq_u32_e32 vcc, 0, v192
	s_and_saveexec_b64 s[0:1], vcc
	global_store_dword v194, v184, s[28:29] offset:0
	global_store_dword v194, v185, s[28:29] offset:16
	global_store_dword v194, v186, s[28:29] offset:32
	global_store_dword v194, v187, s[28:29] offset:48
	global_store_dword v194, v188, s[28:29] offset:64
	global_store_dword v194, v189, s[28:29] offset:80
	global_store_dword v194, v190, s[28:29] offset:96
	global_store_dword v194, v191, s[28:29] offset:112
	s_or_b64 exec, exec, s[0:1]
	ds_write2_b32 v130, v82, v66 offset0:0 offset1:32
	ds_write2_b32 v130, v83, v67 offset0:68 offset1:100
	ds_write2_b32 v130, v84, v68 offset0:136 offset1:168
	ds_write2_b32 v130, v85, v69 offset0:204 offset1:236
	v_add_u32_e32 v130, 0x880, v130
	ds_write2_b32 v130, v86, v70 offset0:0 offset1:32
	ds_write2_b32 v130, v87, v71 offset0:68 offset1:100
	ds_write2_b32 v130, v88, v72 offset0:136 offset1:168
	ds_write2_b32 v130, v89, v73 offset0:204 offset1:236
	v_add_u32_e32 v130, 0x880, v130
	ds_write2_b32 v130, v90, v74 offset0:0 offset1:32
	ds_write2_b32 v130, v91, v75 offset0:68 offset1:100
	ds_write2_b32 v130, v92, v76 offset0:136 offset1:168
	ds_write2_b32 v130, v93, v77 offset0:204 offset1:236
	v_add_u32_e32 v130, 0x880, v130
	ds_write2_b32 v130, v94, v78 offset0:0 offset1:32
	ds_write2_b32 v130, v95, v79 offset0:68 offset1:100
	ds_write2_b32 v130, v96, v80 offset0:136 offset1:168
	ds_write2_b32 v130, v97, v81 offset0:204 offset1:236
	v_subrev_u32_e32 v130, 0x1980, v130
	s_waitcnt lgkmcnt(0)
	ds_read_b128 v[66:69], v131
	ds_read_b128 v[70:73], v131 offset:1088
	ds_read_b128 v[74:77], v131 offset:2176
	ds_read_b128 v[78:81], v131 offset:3264
	ds_read_b128 v[82:85], v131 offset:4352
	ds_read_b128 v[86:89], v131 offset:5440
	ds_read_b128 v[90:93], v131 offset:6528
	ds_read_b128 v[94:97], v131 offset:7616
	s_waitcnt vmcnt(8) lgkmcnt(0)
	v_fma_f32 v66, v66, v180, v148
	v_fma_f32 v67, v67, v181, v149
	v_fma_f32 v68, v68, v182, v150
	v_fma_f32 v69, v69, v183, v151
	global_store_dwordx4 v0, v[66:69], s[38:39] nt
	s_add_u32 s38, s38, 0x4000
	s_addc_u32 s39, s39, 0
	v_mul_f32_e32 v184, v66, v66
	v_fmac_f32_e32 v184, v67, v67
	v_fmac_f32_e32 v184, v68, v68
	v_fmac_f32_e32 v184, v69, v69
	v_fma_f32 v70, v70, v180, v152
	v_fma_f32 v71, v71, v181, v153
	v_fma_f32 v72, v72, v182, v154
	v_fma_f32 v73, v73, v183, v155
	global_store_dwordx4 v0, v[70:73], s[38:39] nt
	s_add_u32 s38, s38, 0x4000
	s_addc_u32 s39, s39, 0
	v_mul_f32_e32 v185, v70, v70
	v_fmac_f32_e32 v185, v71, v71
	v_fmac_f32_e32 v185, v72, v72
	v_fmac_f32_e32 v185, v73, v73
	v_fma_f32 v74, v74, v180, v156
	v_fma_f32 v75, v75, v181, v157
	v_fma_f32 v76, v76, v182, v158
	v_fma_f32 v77, v77, v183, v159
	global_store_dwordx4 v0, v[74:77], s[38:39] nt
	s_add_u32 s38, s38, 0x4000
	s_addc_u32 s39, s39, 0
	v_mul_f32_e32 v186, v74, v74
	v_fmac_f32_e32 v186, v75, v75
	v_fmac_f32_e32 v186, v76, v76
	v_fmac_f32_e32 v186, v77, v77
	v_fma_f32 v78, v78, v180, v160
	v_fma_f32 v79, v79, v181, v161
	v_fma_f32 v80, v80, v182, v162
	v_fma_f32 v81, v81, v183, v163
	global_store_dwordx4 v0, v[78:81], s[38:39] nt
	s_add_u32 s38, s38, 0x4000
	s_addc_u32 s39, s39, 0
	v_mul_f32_e32 v187, v78, v78
	v_fmac_f32_e32 v187, v79, v79
	v_fmac_f32_e32 v187, v80, v80
	v_fmac_f32_e32 v187, v81, v81
	v_fma_f32 v82, v82, v180, v164
	v_fma_f32 v83, v83, v181, v165
	v_fma_f32 v84, v84, v182, v166
	v_fma_f32 v85, v85, v183, v167
	global_store_dwordx4 v0, v[82:85], s[38:39] nt
	s_add_u32 s38, s38, 0x4000
	s_addc_u32 s39, s39, 0
	v_mul_f32_e32 v188, v82, v82
	v_fmac_f32_e32 v188, v83, v83
	v_fmac_f32_e32 v188, v84, v84
	v_fmac_f32_e32 v188, v85, v85
	v_fma_f32 v86, v86, v180, v168
	v_fma_f32 v87, v87, v181, v169
	v_fma_f32 v88, v88, v182, v170
	v_fma_f32 v89, v89, v183, v171
	global_store_dwordx4 v0, v[86:89], s[38:39] nt
	s_add_u32 s38, s38, 0x4000
	s_addc_u32 s39, s39, 0
	v_mul_f32_e32 v189, v86, v86
	v_fmac_f32_e32 v189, v87, v87
	v_fmac_f32_e32 v189, v88, v88
	v_fmac_f32_e32 v189, v89, v89
	v_fma_f32 v90, v90, v180, v172
	v_fma_f32 v91, v91, v181, v173
	v_fma_f32 v92, v92, v182, v174
	v_fma_f32 v93, v93, v183, v175
	global_store_dwordx4 v0, v[90:93], s[38:39] nt
	s_add_u32 s38, s38, 0x4000
	s_addc_u32 s39, s39, 0
	v_mul_f32_e32 v190, v90, v90
	v_fmac_f32_e32 v190, v91, v91
	v_fmac_f32_e32 v190, v92, v92
	v_fmac_f32_e32 v190, v93, v93
	v_fma_f32 v94, v94, v180, v176
	v_fma_f32 v95, v95, v181, v177
	v_fma_f32 v96, v96, v182, v178
	v_fma_f32 v97, v97, v183, v179
	global_store_dwordx4 v0, v[94:97], s[38:39] nt
	s_add_u32 s38, s38, 0x4000
	s_addc_u32 s39, s39, 0
	v_mul_f32_e32 v191, v94, v94
	v_fmac_f32_e32 v191, v95, v95
	v_fmac_f32_e32 v191, v96, v96
	v_fmac_f32_e32 v191, v97, v97
	global_load_dwordx4 v[148:151], v0, s[36:37] nt
	s_add_u32 s36, s36, 0x4000
	s_addc_u32 s37, s37, 0
	global_load_dwordx4 v[152:155], v0, s[36:37] nt
	s_add_u32 s36, s36, 0x4000
	s_addc_u32 s37, s37, 0
	global_load_dwordx4 v[156:159], v0, s[36:37] nt
	s_add_u32 s36, s36, 0x4000
	s_addc_u32 s37, s37, 0
	global_load_dwordx4 v[160:163], v0, s[36:37] nt
	s_add_u32 s36, s36, 0x4000
	s_addc_u32 s37, s37, 0
	global_load_dwordx4 v[164:167], v0, s[36:37] nt
	s_add_u32 s36, s36, 0x4000
	s_addc_u32 s37, s37, 0
	global_load_dwordx4 v[168:171], v0, s[36:37] nt
	s_add_u32 s36, s36, 0x4000
	s_addc_u32 s37, s37, 0
	global_load_dwordx4 v[172:175], v0, s[36:37] nt
	s_add_u32 s36, s36, 0x4000
	s_addc_u32 s37, s37, 0
	global_load_dwordx4 v[176:179], v0, s[36:37] nt
	s_add_u32 s36, s36, 0x4000
	s_addc_u32 s37, s37, 0
	v_add_f32_dpp v184, v184, v184 quad_perm:[1,0,3,2] row_mask:0xf bank_mask:0xf
	v_add_f32_dpp v185, v185, v185 quad_perm:[1,0,3,2] row_mask:0xf bank_mask:0xf
	v_add_f32_dpp v186, v186, v186 quad_perm:[1,0,3,2] row_mask:0xf bank_mask:0xf
	v_add_f32_dpp v187, v187, v187 quad_perm:[1,0,3,2] row_mask:0xf bank_mask:0xf
	v_add_f32_dpp v188, v188, v188 quad_perm:[1,0,3,2] row_mask:0xf bank_mask:0xf
	v_add_f32_dpp v189, v189, v189 quad_perm:[1,0,3,2] row_mask:0xf bank_mask:0xf
	v_add_f32_dpp v190, v190, v190 quad_perm:[1,0,3,2] row_mask:0xf bank_mask:0xf
	v_add_f32_dpp v191, v191, v191 quad_perm:[1,0,3,2] row_mask:0xf bank_mask:0xf
	v_add_f32_dpp v184, v184, v184 quad_perm:[2,3,0,1] row_mask:0xf bank_mask:0xf
	v_add_f32_dpp v185, v185, v185 quad_perm:[2,3,0,1] row_mask:0xf bank_mask:0xf
	v_add_f32_dpp v186, v186, v186 quad_perm:[2,3,0,1] row_mask:0xf bank_mask:0xf
	v_add_f32_dpp v187, v187, v187 quad_perm:[2,3,0,1] row_mask:0xf bank_mask:0xf
	v_add_f32_dpp v188, v188, v188 quad_perm:[2,3,0,1] row_mask:0xf bank_mask:0xf
	v_add_f32_dpp v189, v189, v189 quad_perm:[2,3,0,1] row_mask:0xf bank_mask:0xf
	v_add_f32_dpp v190, v190, v190 quad_perm:[2,3,0,1] row_mask:0xf bank_mask:0xf
	v_add_f32_dpp v191, v191, v191 quad_perm:[2,3,0,1] row_mask:0xf bank_mask:0xf
	v_add_f32_dpp v184, v184, v184 row_half_mirror row_mask:0xf bank_mask:0xf
	v_add_f32_dpp v185, v185, v185 row_half_mirror row_mask:0xf bank_mask:0xf
	v_add_f32_dpp v186, v186, v186 row_half_mirror row_mask:0xf bank_mask:0xf
	v_add_f32_dpp v187, v187, v187 row_half_mirror row_mask:0xf bank_mask:0xf
	v_add_f32_dpp v188, v188, v188 row_half_mirror row_mask:0xf bank_mask:0xf
	v_add_f32_dpp v189, v189, v189 row_half_mirror row_mask:0xf bank_mask:0xf
	v_add_f32_dpp v190, v190, v190 row_half_mirror row_mask:0xf bank_mask:0xf
	v_add_f32_dpp v191, v191, v191 row_half_mirror row_mask:0xf bank_mask:0xf
	v_add_f32_dpp v184, v184, v184 row_mirror row_mask:0xf bank_mask:0xf
	v_add_f32_dpp v185, v185, v185 row_mirror row_mask:0xf bank_mask:0xf
	v_add_f32_dpp v186, v186, v186 row_mirror row_mask:0xf bank_mask:0xf
	v_add_f32_dpp v187, v187, v187 row_mirror row_mask:0xf bank_mask:0xf
	v_add_f32_dpp v188, v188, v188 row_mirror row_mask:0xf bank_mask:0xf
	v_add_f32_dpp v189, v189, v189 row_mirror row_mask:0xf bank_mask:0xf
	v_add_f32_dpp v190, v190, v190 row_mirror row_mask:0xf bank_mask:0xf
	v_add_f32_dpp v191, v191, v191 row_mirror row_mask:0xf bank_mask:0xf
	v_cmp_eq_u32_e32 vcc, 0, v192
	s_and_saveexec_b64 s[0:1], vcc
	global_store_dword v194, v184, s[28:29] offset:128
	global_store_dword v194, v185, s[28:29] offset:144
	global_store_dword v194, v186, s[28:29] offset:160
	global_store_dword v194, v187, s[28:29] offset:176
	global_store_dword v194, v188, s[28:29] offset:192
	global_store_dword v194, v189, s[28:29] offset:208
	global_store_dword v194, v190, s[28:29] offset:224
	global_store_dword v194, v191, s[28:29] offset:240
	s_or_b64 exec, exec, s[0:1]
	ds_write2_b32 v130, v50, v34 offset0:0 offset1:32
	ds_write2_b32 v130, v51, v35 offset0:68 offset1:100
	ds_write2_b32 v130, v52, v36 offset0:136 offset1:168
	ds_write2_b32 v130, v53, v37 offset0:204 offset1:236
	v_add_u32_e32 v130, 0x880, v130
	ds_write2_b32 v130, v54, v38 offset0:0 offset1:32
	ds_write2_b32 v130, v55, v39 offset0:68 offset1:100
	ds_write2_b32 v130, v56, v40 offset0:136 offset1:168
	ds_write2_b32 v130, v57, v41 offset0:204 offset1:236
	v_add_u32_e32 v130, 0x880, v130
	ds_write2_b32 v130, v58, v42 offset0:0 offset1:32
	ds_write2_b32 v130, v59, v43 offset0:68 offset1:100
	ds_write2_b32 v130, v60, v44 offset0:136 offset1:168
	ds_write2_b32 v130, v61, v45 offset0:204 offset1:236
	v_add_u32_e32 v130, 0x880, v130
	ds_write2_b32 v130, v62, v46 offset0:0 offset1:32
	ds_write2_b32 v130, v63, v47 offset0:68 offset1:100
	ds_write2_b32 v130, v64, v48 offset0:136 offset1:168
	ds_write2_b32 v130, v65, v49 offset0:204 offset1:236
	v_subrev_u32_e32 v130, 0x1980, v130
	s_waitcnt lgkmcnt(0)
	ds_read_b128 v[34:37], v131
	ds_read_b128 v[38:41], v131 offset:1088
	ds_read_b128 v[42:45], v131 offset:2176
	ds_read_b128 v[46:49], v131 offset:3264
	ds_read_b128 v[50:53], v131 offset:4352
	ds_read_b128 v[54:57], v131 offset:5440
	ds_read_b128 v[58:61], v131 offset:6528
	ds_read_b128 v[62:65], v131 offset:7616
	s_waitcnt vmcnt(8) lgkmcnt(0)
	v_fma_f32 v34, v34, v180, v148
	v_fma_f32 v35, v35, v181, v149
	v_fma_f32 v36, v36, v182, v150
	v_fma_f32 v37, v37, v183, v151
	global_store_dwordx4 v0, v[34:37], s[38:39] nt
	s_add_u32 s38, s38, 0x4000
	s_addc_u32 s39, s39, 0
	v_mul_f32_e32 v184, v34, v34
	v_fmac_f32_e32 v184, v35, v35
	v_fmac_f32_e32 v184, v36, v36
	v_fmac_f32_e32 v184, v37, v37
	v_fma_f32 v38, v38, v180, v152
	v_fma_f32 v39, v39, v181, v153
	v_fma_f32 v40, v40, v182, v154
	v_fma_f32 v41, v41, v183, v155
	global_store_dwordx4 v0, v[38:41], s[38:39] nt
	s_add_u32 s38, s38, 0x4000
	s_addc_u32 s39, s39, 0
	v_mul_f32_e32 v185, v38, v38
	v_fmac_f32_e32 v185, v39, v39
	v_fmac_f32_e32 v185, v40, v40
	v_fmac_f32_e32 v185, v41, v41
	v_fma_f32 v42, v42, v180, v156
	v_fma_f32 v43, v43, v181, v157
	v_fma_f32 v44, v44, v182, v158
	v_fma_f32 v45, v45, v183, v159
	global_store_dwordx4 v0, v[42:45], s[38:39] nt
	s_add_u32 s38, s38, 0x4000
	s_addc_u32 s39, s39, 0
	v_mul_f32_e32 v186, v42, v42
	v_fmac_f32_e32 v186, v43, v43
	v_fmac_f32_e32 v186, v44, v44
	v_fmac_f32_e32 v186, v45, v45
	v_fma_f32 v46, v46, v180, v160
	v_fma_f32 v47, v47, v181, v161
	v_fma_f32 v48, v48, v182, v162
	v_fma_f32 v49, v49, v183, v163
	global_store_dwordx4 v0, v[46:49], s[38:39] nt
	s_add_u32 s38, s38, 0x4000
	s_addc_u32 s39, s39, 0
	v_mul_f32_e32 v187, v46, v46
	v_fmac_f32_e32 v187, v47, v47
	v_fmac_f32_e32 v187, v48, v48
	v_fmac_f32_e32 v187, v49, v49
	v_fma_f32 v50, v50, v180, v164
	v_fma_f32 v51, v51, v181, v165
	v_fma_f32 v52, v52, v182, v166
	v_fma_f32 v53, v53, v183, v167
	global_store_dwordx4 v0, v[50:53], s[38:39] nt
	s_add_u32 s38, s38, 0x4000
	s_addc_u32 s39, s39, 0
	v_mul_f32_e32 v188, v50, v50
	v_fmac_f32_e32 v188, v51, v51
	v_fmac_f32_e32 v188, v52, v52
	v_fmac_f32_e32 v188, v53, v53
	v_fma_f32 v54, v54, v180, v168
	v_fma_f32 v55, v55, v181, v169
	v_fma_f32 v56, v56, v182, v170
	v_fma_f32 v57, v57, v183, v171
	global_store_dwordx4 v0, v[54:57], s[38:39] nt
	s_add_u32 s38, s38, 0x4000
	s_addc_u32 s39, s39, 0
	v_mul_f32_e32 v189, v54, v54
	v_fmac_f32_e32 v189, v55, v55
	v_fmac_f32_e32 v189, v56, v56
	v_fmac_f32_e32 v189, v57, v57
	v_fma_f32 v58, v58, v180, v172
	v_fma_f32 v59, v59, v181, v173
	v_fma_f32 v60, v60, v182, v174
	v_fma_f32 v61, v61, v183, v175
	global_store_dwordx4 v0, v[58:61], s[38:39] nt
	s_add_u32 s38, s38, 0x4000
	s_addc_u32 s39, s39, 0
	v_mul_f32_e32 v190, v58, v58
	v_fmac_f32_e32 v190, v59, v59
	v_fmac_f32_e32 v190, v60, v60
	v_fmac_f32_e32 v190, v61, v61
	v_fma_f32 v62, v62, v180, v176
	v_fma_f32 v63, v63, v181, v177
	v_fma_f32 v64, v64, v182, v178
	v_fma_f32 v65, v65, v183, v179
	global_store_dwordx4 v0, v[62:65], s[38:39] nt
	s_add_u32 s38, s38, 0x4000
	s_addc_u32 s39, s39, 0
	v_mul_f32_e32 v191, v62, v62
	v_fmac_f32_e32 v191, v63, v63
	v_fmac_f32_e32 v191, v64, v64
	v_fmac_f32_e32 v191, v65, v65
	global_load_dwordx4 v[148:151], v0, s[36:37] nt
	s_add_u32 s36, s36, 0x4000
	s_addc_u32 s37, s37, 0
	global_load_dwordx4 v[152:155], v0, s[36:37] nt
	s_add_u32 s36, s36, 0x4000
	s_addc_u32 s37, s37, 0
	global_load_dwordx4 v[156:159], v0, s[36:37] nt
	s_add_u32 s36, s36, 0x4000
	s_addc_u32 s37, s37, 0
	global_load_dwordx4 v[160:163], v0, s[36:37] nt
	s_add_u32 s36, s36, 0x4000
	s_addc_u32 s37, s37, 0
	global_load_dwordx4 v[164:167], v0, s[36:37] nt
	s_add_u32 s36, s36, 0x4000
	s_addc_u32 s37, s37, 0
	global_load_dwordx4 v[168:171], v0, s[36:37] nt
	s_add_u32 s36, s36, 0x4000
	s_addc_u32 s37, s37, 0
	global_load_dwordx4 v[172:175], v0, s[36:37] nt
	s_add_u32 s36, s36, 0x4000
	s_addc_u32 s37, s37, 0
	global_load_dwordx4 v[176:179], v0, s[36:37] nt
	s_add_u32 s36, s36, 0x4000
	s_addc_u32 s37, s37, 0
	v_add_f32_dpp v184, v184, v184 quad_perm:[1,0,3,2] row_mask:0xf bank_mask:0xf
	v_add_f32_dpp v185, v185, v185 quad_perm:[1,0,3,2] row_mask:0xf bank_mask:0xf
	v_add_f32_dpp v186, v186, v186 quad_perm:[1,0,3,2] row_mask:0xf bank_mask:0xf
	v_add_f32_dpp v187, v187, v187 quad_perm:[1,0,3,2] row_mask:0xf bank_mask:0xf
	v_add_f32_dpp v188, v188, v188 quad_perm:[1,0,3,2] row_mask:0xf bank_mask:0xf
	v_add_f32_dpp v189, v189, v189 quad_perm:[1,0,3,2] row_mask:0xf bank_mask:0xf
	v_add_f32_dpp v190, v190, v190 quad_perm:[1,0,3,2] row_mask:0xf bank_mask:0xf
	v_add_f32_dpp v191, v191, v191 quad_perm:[1,0,3,2] row_mask:0xf bank_mask:0xf
	v_add_f32_dpp v184, v184, v184 quad_perm:[2,3,0,1] row_mask:0xf bank_mask:0xf
	v_add_f32_dpp v185, v185, v185 quad_perm:[2,3,0,1] row_mask:0xf bank_mask:0xf
	v_add_f32_dpp v186, v186, v186 quad_perm:[2,3,0,1] row_mask:0xf bank_mask:0xf
	v_add_f32_dpp v187, v187, v187 quad_perm:[2,3,0,1] row_mask:0xf bank_mask:0xf
	v_add_f32_dpp v188, v188, v188 quad_perm:[2,3,0,1] row_mask:0xf bank_mask:0xf
	v_add_f32_dpp v189, v189, v189 quad_perm:[2,3,0,1] row_mask:0xf bank_mask:0xf
	v_add_f32_dpp v190, v190, v190 quad_perm:[2,3,0,1] row_mask:0xf bank_mask:0xf
	v_add_f32_dpp v191, v191, v191 quad_perm:[2,3,0,1] row_mask:0xf bank_mask:0xf
	v_add_f32_dpp v184, v184, v184 row_half_mirror row_mask:0xf bank_mask:0xf
	v_add_f32_dpp v185, v185, v185 row_half_mirror row_mask:0xf bank_mask:0xf
	v_add_f32_dpp v186, v186, v186 row_half_mirror row_mask:0xf bank_mask:0xf
	v_add_f32_dpp v187, v187, v187 row_half_mirror row_mask:0xf bank_mask:0xf
	v_add_f32_dpp v188, v188, v188 row_half_mirror row_mask:0xf bank_mask:0xf
	v_add_f32_dpp v189, v189, v189 row_half_mirror row_mask:0xf bank_mask:0xf
	v_add_f32_dpp v190, v190, v190 row_half_mirror row_mask:0xf bank_mask:0xf
	v_add_f32_dpp v191, v191, v191 row_half_mirror row_mask:0xf bank_mask:0xf
	v_add_f32_dpp v184, v184, v184 row_mirror row_mask:0xf bank_mask:0xf
	v_add_f32_dpp v185, v185, v185 row_mirror row_mask:0xf bank_mask:0xf
	v_add_f32_dpp v186, v186, v186 row_mirror row_mask:0xf bank_mask:0xf
	v_add_f32_dpp v187, v187, v187 row_mirror row_mask:0xf bank_mask:0xf
	v_add_f32_dpp v188, v188, v188 row_mirror row_mask:0xf bank_mask:0xf
	v_add_f32_dpp v189, v189, v189 row_mirror row_mask:0xf bank_mask:0xf
	v_add_f32_dpp v190, v190, v190 row_mirror row_mask:0xf bank_mask:0xf
	v_add_f32_dpp v191, v191, v191 row_mirror row_mask:0xf bank_mask:0xf
	v_cmp_eq_u32_e32 vcc, 0, v192
	s_and_saveexec_b64 s[0:1], vcc
	global_store_dword v194, v184, s[28:29] offset:256
	global_store_dword v194, v185, s[28:29] offset:272
	global_store_dword v194, v186, s[28:29] offset:288
	global_store_dword v194, v187, s[28:29] offset:304
	global_store_dword v194, v188, s[28:29] offset:320
	global_store_dword v194, v189, s[28:29] offset:336
	global_store_dword v194, v190, s[28:29] offset:352
	global_store_dword v194, v191, s[28:29] offset:368
	s_or_b64 exec, exec, s[0:1]
	ds_write2_b32 v130, v18, v2 offset0:0 offset1:32
	ds_write2_b32 v130, v19, v3 offset0:68 offset1:100
	ds_write2_b32 v130, v20, v4 offset0:136 offset1:168
	ds_write2_b32 v130, v21, v5 offset0:204 offset1:236
	v_add_u32_e32 v130, 0x880, v130
	ds_write2_b32 v130, v22, v6 offset0:0 offset1:32
	ds_write2_b32 v130, v23, v7 offset0:68 offset1:100
	ds_write2_b32 v130, v24, v8 offset0:136 offset1:168
	ds_write2_b32 v130, v25, v9 offset0:204 offset1:236
	v_add_u32_e32 v130, 0x880, v130
	ds_write2_b32 v130, v26, v10 offset0:0 offset1:32
	ds_write2_b32 v130, v27, v11 offset0:68 offset1:100
	ds_write2_b32 v130, v28, v12 offset0:136 offset1:168
	ds_write2_b32 v130, v29, v13 offset0:204 offset1:236
	v_add_u32_e32 v130, 0x880, v130
	ds_write2_b32 v130, v30, v14 offset0:0 offset1:32
	ds_write2_b32 v130, v31, v15 offset0:68 offset1:100
	ds_write2_b32 v130, v32, v16 offset0:136 offset1:168
	ds_write2_b32 v130, v33, v17 offset0:204 offset1:236
	v_subrev_u32_e32 v130, 0x1980, v130
	s_waitcnt lgkmcnt(0)
	ds_read_b128 v[132:135], v131
	ds_read_b128 v[136:139], v131 offset:1088
	ds_read_b128 v[140:143], v131 offset:2176
	ds_read_b128 v[144:147], v131 offset:3264
	ds_read_b128 v[18:21], v131 offset:4352
	ds_read_b128 v[22:25], v131 offset:5440
	ds_read_b128 v[26:29], v131 offset:6528
	ds_read_b128 v[30:33], v131 offset:7616
	s_waitcnt vmcnt(8) lgkmcnt(0)
	v_fma_f32 v132, v132, v180, v148
	v_fma_f32 v133, v133, v181, v149
	v_fma_f32 v134, v134, v182, v150
	v_fma_f32 v135, v135, v183, v151
	global_store_dwordx4 v0, v[132:135], s[38:39] nt
	s_add_u32 s38, s38, 0x4000
	s_addc_u32 s39, s39, 0
	v_mul_f32_e32 v184, v132, v132
	v_fmac_f32_e32 v184, v133, v133
	v_fmac_f32_e32 v184, v134, v134
	v_fmac_f32_e32 v184, v135, v135
	v_fma_f32 v136, v136, v180, v152
	v_fma_f32 v137, v137, v181, v153
	v_fma_f32 v138, v138, v182, v154
	v_fma_f32 v139, v139, v183, v155
	global_store_dwordx4 v0, v[136:139], s[38:39] nt
	s_add_u32 s38, s38, 0x4000
	s_addc_u32 s39, s39, 0
	v_mul_f32_e32 v185, v136, v136
	v_fmac_f32_e32 v185, v137, v137
	v_fmac_f32_e32 v185, v138, v138
	v_fmac_f32_e32 v185, v139, v139
	v_fma_f32 v140, v140, v180, v156
	v_fma_f32 v141, v141, v181, v157
	v_fma_f32 v142, v142, v182, v158
	v_fma_f32 v143, v143, v183, v159
	global_store_dwordx4 v0, v[140:143], s[38:39] nt
	s_add_u32 s38, s38, 0x4000
	s_addc_u32 s39, s39, 0
	v_mul_f32_e32 v186, v140, v140
	v_fmac_f32_e32 v186, v141, v141
	v_fmac_f32_e32 v186, v142, v142
	v_fmac_f32_e32 v186, v143, v143
	v_fma_f32 v144, v144, v180, v160
	v_fma_f32 v145, v145, v181, v161
	v_fma_f32 v146, v146, v182, v162
	v_fma_f32 v147, v147, v183, v163
	global_store_dwordx4 v0, v[144:147], s[38:39] nt
	s_add_u32 s38, s38, 0x4000
	s_addc_u32 s39, s39, 0
	v_mul_f32_e32 v187, v144, v144
	v_fmac_f32_e32 v187, v145, v145
	v_fmac_f32_e32 v187, v146, v146
	v_fmac_f32_e32 v187, v147, v147
	v_fma_f32 v18, v18, v180, v164
	v_fma_f32 v19, v19, v181, v165
	v_fma_f32 v20, v20, v182, v166
	v_fma_f32 v21, v21, v183, v167
	global_store_dwordx4 v0, v[18:21], s[38:39] nt
	s_add_u32 s38, s38, 0x4000
	s_addc_u32 s39, s39, 0
	v_mul_f32_e32 v188, v18, v18
	v_fmac_f32_e32 v188, v19, v19
	v_fmac_f32_e32 v188, v20, v20
	v_fmac_f32_e32 v188, v21, v21
	v_fma_f32 v22, v22, v180, v168
	v_fma_f32 v23, v23, v181, v169
	v_fma_f32 v24, v24, v182, v170
	v_fma_f32 v25, v25, v183, v171
	global_store_dwordx4 v0, v[22:25], s[38:39] nt
	s_add_u32 s38, s38, 0x4000
	s_addc_u32 s39, s39, 0
	v_mul_f32_e32 v189, v22, v22
	v_fmac_f32_e32 v189, v23, v23
	v_fmac_f32_e32 v189, v24, v24
	v_fmac_f32_e32 v189, v25, v25
	v_fma_f32 v26, v26, v180, v172
	v_fma_f32 v27, v27, v181, v173
	v_fma_f32 v28, v28, v182, v174
	v_fma_f32 v29, v29, v183, v175
	global_store_dwordx4 v0, v[26:29], s[38:39] nt
	s_add_u32 s38, s38, 0x4000
	s_addc_u32 s39, s39, 0
	v_mul_f32_e32 v190, v26, v26
	v_fmac_f32_e32 v190, v27, v27
	v_fmac_f32_e32 v190, v28, v28
	v_fmac_f32_e32 v190, v29, v29
	v_fma_f32 v30, v30, v180, v176
	v_fma_f32 v31, v31, v181, v177
	v_fma_f32 v32, v32, v182, v178
	v_fma_f32 v33, v33, v183, v179
	global_store_dwordx4 v0, v[30:33], s[38:39] nt
	s_add_u32 s38, s38, 0x4000
	s_addc_u32 s39, s39, 0
	v_mul_f32_e32 v191, v30, v30
	v_fmac_f32_e32 v191, v31, v31
	v_fmac_f32_e32 v191, v32, v32
	v_fmac_f32_e32 v191, v33, v33
	v_add_f32_dpp v184, v184, v184 quad_perm:[1,0,3,2] row_mask:0xf bank_mask:0xf
	v_add_f32_dpp v185, v185, v185 quad_perm:[1,0,3,2] row_mask:0xf bank_mask:0xf
	v_add_f32_dpp v186, v186, v186 quad_perm:[1,0,3,2] row_mask:0xf bank_mask:0xf
	v_add_f32_dpp v187, v187, v187 quad_perm:[1,0,3,2] row_mask:0xf bank_mask:0xf
	v_add_f32_dpp v188, v188, v188 quad_perm:[1,0,3,2] row_mask:0xf bank_mask:0xf
	v_add_f32_dpp v189, v189, v189 quad_perm:[1,0,3,2] row_mask:0xf bank_mask:0xf
	v_add_f32_dpp v190, v190, v190 quad_perm:[1,0,3,2] row_mask:0xf bank_mask:0xf
	v_add_f32_dpp v191, v191, v191 quad_perm:[1,0,3,2] row_mask:0xf bank_mask:0xf
	v_add_f32_dpp v184, v184, v184 quad_perm:[2,3,0,1] row_mask:0xf bank_mask:0xf
	v_add_f32_dpp v185, v185, v185 quad_perm:[2,3,0,1] row_mask:0xf bank_mask:0xf
	v_add_f32_dpp v186, v186, v186 quad_perm:[2,3,0,1] row_mask:0xf bank_mask:0xf
	v_add_f32_dpp v187, v187, v187 quad_perm:[2,3,0,1] row_mask:0xf bank_mask:0xf
	v_add_f32_dpp v188, v188, v188 quad_perm:[2,3,0,1] row_mask:0xf bank_mask:0xf
	v_add_f32_dpp v189, v189, v189 quad_perm:[2,3,0,1] row_mask:0xf bank_mask:0xf
	v_add_f32_dpp v190, v190, v190 quad_perm:[2,3,0,1] row_mask:0xf bank_mask:0xf
	v_add_f32_dpp v191, v191, v191 quad_perm:[2,3,0,1] row_mask:0xf bank_mask:0xf
	v_add_f32_dpp v184, v184, v184 row_half_mirror row_mask:0xf bank_mask:0xf
	v_add_f32_dpp v185, v185, v185 row_half_mirror row_mask:0xf bank_mask:0xf
	v_add_f32_dpp v186, v186, v186 row_half_mirror row_mask:0xf bank_mask:0xf
	v_add_f32_dpp v187, v187, v187 row_half_mirror row_mask:0xf bank_mask:0xf
	v_add_f32_dpp v188, v188, v188 row_half_mirror row_mask:0xf bank_mask:0xf
	v_add_f32_dpp v189, v189, v189 row_half_mirror row_mask:0xf bank_mask:0xf
	v_add_f32_dpp v190, v190, v190 row_half_mirror row_mask:0xf bank_mask:0xf
	v_add_f32_dpp v191, v191, v191 row_half_mirror row_mask:0xf bank_mask:0xf
	v_add_f32_dpp v184, v184, v184 row_mirror row_mask:0xf bank_mask:0xf
	v_add_f32_dpp v185, v185, v185 row_mirror row_mask:0xf bank_mask:0xf
	v_add_f32_dpp v186, v186, v186 row_mirror row_mask:0xf bank_mask:0xf
	v_add_f32_dpp v187, v187, v187 row_mirror row_mask:0xf bank_mask:0xf
	v_add_f32_dpp v188, v188, v188 row_mirror row_mask:0xf bank_mask:0xf
	v_add_f32_dpp v189, v189, v189 row_mirror row_mask:0xf bank_mask:0xf
	v_add_f32_dpp v190, v190, v190 row_mirror row_mask:0xf bank_mask:0xf
	v_add_f32_dpp v191, v191, v191 row_mirror row_mask:0xf bank_mask:0xf
	v_cmp_eq_u32_e32 vcc, 0, v192
	s_and_saveexec_b64 s[0:1], vcc
	global_store_dword v194, v184, s[28:29] offset:384
	global_store_dword v194, v185, s[28:29] offset:400
	global_store_dword v194, v186, s[28:29] offset:416
	global_store_dword v194, v187, s[28:29] offset:432
	global_store_dword v194, v188, s[28:29] offset:448
	global_store_dword v194, v189, s[28:29] offset:464
	global_store_dword v194, v190, s[28:29] offset:480
	global_store_dword v194, v191, s[28:29] offset:496
	s_or_b64 exec, exec, s[0:1]
	s_add_i32 s34, s34, s30
	s_cmp_ge_i32 s34, s35
	s_cbranch_scc0 .LBB0_52

.LBB0_195:
	s_andn2_b64 vcc, exec, s[0:1]
	s_cbranch_vccnz .LBB0_301
	s_cmp_lg_u32 s2, 1
	s_mov_b64 s[0:1], -1
	s_cbranch_scc0 .LBB0_207
	s_cmp_lt_i32 s96, 1
	s_cbranch_scc1 .Lmy_norm_plain
	v_readlane_b32 s0, v243, 0
	v_and_b32_e32 v189, 63, v200
	v_lshrrev_b32_e32 v190, 4, v189
	v_and_b32_e32 v191, 15, v189
	v_lshrrev_b32_e32 v192, 6, v200
	s_and_b32 s1, s0, 7
	s_lshl_b32 s1, s1, 3
	s_lshr_b32 s2, s0, 6
	s_add_u32 s1, s1, s2
	s_lshl_b32 s1, s1, 8
	s_bfe_u32 s2, s0, 0x30003
	s_lshl_b32 s2, s2, 7
	v_lshrrev_b32_e32 v193, 1, v192
	v_and_b32_e32 v192, 1, v192
	v_lshl_add_u32 v193, v193, 7, s1
	v_lshl_add_u32 v192, v192, 6, s2
	v_lshl_add_u32 v192, v191, 2, v192
	v_add_u32_e32 v193, v193, v190
	s_lshr_b32 s3, s1, 12
	s_lshl_b32 s4, s96, 2
	s_add_u32 s3, s3, s4
	s_mul_i32 s3, s3, 0x3000
	v_readlane_b32 s4, v243, 7
	v_readlane_b32 s5, v243, 8
	s_add_u32 s4, s4, s3
	s_addc_u32 s5, s5, 0
	s_lshl_b32 s6, s96, 12
	s_add_u32 s6, s16, s6
	s_addc_u32 s7, s17, 0
	v_lshlrev_b32_e32 v194, 2, v192
	global_load_dwordx4 v[180:183], v194, s[6:7]
	s_add_u32 s38, s4, 0x1000
	s_addc_u32 s39, s5, 0
	global_load_dwordx4 v[196:199], v194, s[38:39]
	global_load_dwordx4 v[184:187], v194, s[4:5]
	v_lshl_add_u32 v194, v191, 14, v193
	v_lshlrev_b32_e32 v194, 2, v194
	v_readlane_b32 s8, v243, 5
	v_readlane_b32 s9, v243, 6
	s_nop 4
	global_load_dword v148, v194, s[8:9] offset:0
	global_load_dword v149, v194, s[8:9] offset:16
	global_load_dword v150, v194, s[8:9] offset:32
	global_load_dword v151, v194, s[8:9] offset:48
	global_load_dword v152, v194, s[8:9] offset:64
	global_load_dword v153, v194, s[8:9] offset:80
	global_load_dword v154, v194, s[8:9] offset:96
	global_load_dword v155, v194, s[8:9] offset:112
	global_load_dword v156, v194, s[8:9] offset:128
	global_load_dword v157, v194, s[8:9] offset:144
	global_load_dword v158, v194, s[8:9] offset:160
	global_load_dword v159, v194, s[8:9] offset:176
	global_load_dword v160, v194, s[8:9] offset:192
	global_load_dword v161, v194, s[8:9] offset:208
	global_load_dword v162, v194, s[8:9] offset:224
	global_load_dword v163, v194, s[8:9] offset:240
	global_load_dword v164, v194, s[8:9] offset:256
	global_load_dword v165, v194, s[8:9] offset:272
	global_load_dword v166, v194, s[8:9] offset:288
	global_load_dword v167, v194, s[8:9] offset:304
	global_load_dword v168, v194, s[8:9] offset:320
	global_load_dword v169, v194, s[8:9] offset:336
	global_load_dword v170, v194, s[8:9] offset:352
	global_load_dword v171, v194, s[8:9] offset:368
	global_load_dword v172, v194, s[8:9] offset:384
	global_load_dword v173, v194, s[8:9] offset:400
	global_load_dword v174, v194, s[8:9] offset:416
	global_load_dword v175, v194, s[8:9] offset:432
	global_load_dword v176, v194, s[8:9] offset:448
	global_load_dword v177, v194, s[8:9] offset:464
	global_load_dword v178, v194, s[8:9] offset:480
	global_load_dword v179, v194, s[8:9] offset:496
	v_lshrrev_b32_e32 v188, 1, v193
	v_lshlrev_b32_e32 v188, 5, v188
	v_lshrrev_b32_e32 v190, 5, v192
	v_add_u32_e32 v188, v188, v190
	v_lshlrev_b32_e32 v188, 6, v188
	v_and_b32_e32 v190, 1, v193
	v_lshl_add_u32 v188, v190, 5, v188
	v_and_b32_e32 v190, 31, v192
	v_add_u32_e32 v188, v188, v190
	v_lshlrev_b32_e32 v188, 1, v188
	s_mov_b64 s[36:37], s[62:63]
	s_waitcnt vmcnt(32)
	v_add_f32_e32 v196, 1.0, v196
	v_add_f32_e32 v197, 1.0, v197
	v_add_f32_e32 v198, 1.0, v198
	v_add_f32_e32 v199, 1.0, v199
	v_mul_f32_e32 v180, v180, v196
	v_mul_f32_e32 v181, v181, v197
	v_mul_f32_e32 v182, v182, v198
	v_mul_f32_e32 v183, v183, v199
	s_waitcnt vmcnt(0)
	v_add_f32_dpp v148, v148, v148 quad_perm:[1,0,3,2] row_mask:0xf bank_mask:0xf
	v_add_f32_dpp v149, v149, v149 quad_perm:[1,0,3,2] row_mask:0xf bank_mask:0xf
	v_add_f32_dpp v150, v150, v150 quad_perm:[1,0,3,2] row_mask:0xf bank_mask:0xf
	v_add_f32_dpp v151, v151, v151 quad_perm:[1,0,3,2] row_mask:0xf bank_mask:0xf
	v_add_f32_dpp v152, v152, v152 quad_perm:[1,0,3,2] row_mask:0xf bank_mask:0xf
	v_add_f32_dpp v153, v153, v153 quad_perm:[1,0,3,2] row_mask:0xf bank_mask:0xf
	v_add_f32_dpp v154, v154, v154 quad_perm:[1,0,3,2] row_mask:0xf bank_mask:0xf
	v_add_f32_dpp v155, v155, v155 quad_perm:[1,0,3,2] row_mask:0xf bank_mask:0xf
	v_add_f32_dpp v156, v156, v156 quad_perm:[1,0,3,2] row_mask:0xf bank_mask:0xf
	v_add_f32_dpp v157, v157, v157 quad_perm:[1,0,3,2] row_mask:0xf bank_mask:0xf
	v_add_f32_dpp v158, v158, v158 quad_perm:[1,0,3,2] row_mask:0xf bank_mask:0xf
	v_add_f32_dpp v159, v159, v159 quad_perm:[1,0,3,2] row_mask:0xf bank_mask:0xf
	v_add_f32_dpp v160, v160, v160 quad_perm:[1,0,3,2] row_mask:0xf bank_mask:0xf
	v_add_f32_dpp v161, v161, v161 quad_perm:[1,0,3,2] row_mask:0xf bank_mask:0xf
	v_add_f32_dpp v162, v162, v162 quad_perm:[1,0,3,2] row_mask:0xf bank_mask:0xf
	v_add_f32_dpp v163, v163, v163 quad_perm:[1,0,3,2] row_mask:0xf bank_mask:0xf
	v_add_f32_dpp v164, v164, v164 quad_perm:[1,0,3,2] row_mask:0xf bank_mask:0xf
	v_add_f32_dpp v165, v165, v165 quad_perm:[1,0,3,2] row_mask:0xf bank_mask:0xf
	v_add_f32_dpp v166, v166, v166 quad_perm:[1,0,3,2] row_mask:0xf bank_mask:0xf
	v_add_f32_dpp v167, v167, v167 quad_perm:[1,0,3,2] row_mask:0xf bank_mask:0xf
	v_add_f32_dpp v168, v168, v168 quad_perm:[1,0,3,2] row_mask:0xf bank_mask:0xf
	v_add_f32_dpp v169, v169, v169 quad_perm:[1,0,3,2] row_mask:0xf bank_mask:0xf
	v_add_f32_dpp v170, v170, v170 quad_perm:[1,0,3,2] row_mask:0xf bank_mask:0xf
	v_add_f32_dpp v171, v171, v171 quad_perm:[1,0,3,2] row_mask:0xf bank_mask:0xf
	v_add_f32_dpp v172, v172, v172 quad_perm:[1,0,3,2] row_mask:0xf bank_mask:0xf
	v_add_f32_dpp v173, v173, v173 quad_perm:[1,0,3,2] row_mask:0xf bank_mask:0xf
	v_add_f32_dpp v174, v174, v174 quad_perm:[1,0,3,2] row_mask:0xf bank_mask:0xf
	v_add_f32_dpp v175, v175, v175 quad_perm:[1,0,3,2] row_mask:0xf bank_mask:0xf
	v_add_f32_dpp v176, v176, v176 quad_perm:[1,0,3,2] row_mask:0xf bank_mask:0xf
	v_add_f32_dpp v177, v177, v177 quad_perm:[1,0,3,2] row_mask:0xf bank_mask:0xf
	v_add_f32_dpp v178, v178, v178 quad_perm:[1,0,3,2] row_mask:0xf bank_mask:0xf
	v_add_f32_dpp v179, v179, v179 quad_perm:[1,0,3,2] row_mask:0xf bank_mask:0xf
	v_add_f32_dpp v148, v148, v148 quad_perm:[2,3,0,1] row_mask:0xf bank_mask:0xf
	v_add_f32_dpp v149, v149, v149 quad_perm:[2,3,0,1] row_mask:0xf bank_mask:0xf
	v_add_f32_dpp v150, v150, v150 quad_perm:[2,3,0,1] row_mask:0xf bank_mask:0xf
	v_add_f32_dpp v151, v151, v151 quad_perm:[2,3,0,1] row_mask:0xf bank_mask:0xf
	v_add_f32_dpp v152, v152, v152 quad_perm:[2,3,0,1] row_mask:0xf bank_mask:0xf
	v_add_f32_dpp v153, v153, v153 quad_perm:[2,3,0,1] row_mask:0xf bank_mask:0xf
	v_add_f32_dpp v154, v154, v154 quad_perm:[2,3,0,1] row_mask:0xf bank_mask:0xf
	v_add_f32_dpp v155, v155, v155 quad_perm:[2,3,0,1] row_mask:0xf bank_mask:0xf
	v_add_f32_dpp v156, v156, v156 quad_perm:[2,3,0,1] row_mask:0xf bank_mask:0xf
	v_add_f32_dpp v157, v157, v157 quad_perm:[2,3,0,1] row_mask:0xf bank_mask:0xf
	v_add_f32_dpp v158, v158, v158 quad_perm:[2,3,0,1] row_mask:0xf bank_mask:0xf
	v_add_f32_dpp v159, v159, v159 quad_perm:[2,3,0,1] row_mask:0xf bank_mask:0xf
	v_add_f32_dpp v160, v160, v160 quad_perm:[2,3,0,1] row_mask:0xf bank_mask:0xf
	v_add_f32_dpp v161, v161, v161 quad_perm:[2,3,0,1] row_mask:0xf bank_mask:0xf
	v_add_f32_dpp v162, v162, v162 quad_perm:[2,3,0,1] row_mask:0xf bank_mask:0xf
	v_add_f32_dpp v163, v163, v163 quad_perm:[2,3,0,1] row_mask:0xf bank_mask:0xf
	v_add_f32_dpp v164, v164, v164 quad_perm:[2,3,0,1] row_mask:0xf bank_mask:0xf
	v_add_f32_dpp v165, v165, v165 quad_perm:[2,3,0,1] row_mask:0xf bank_mask:0xf
	v_add_f32_dpp v166, v166, v166 quad_perm:[2,3,0,1] row_mask:0xf bank_mask:0xf
	v_add_f32_dpp v167, v167, v167 quad_perm:[2,3,0,1] row_mask:0xf bank_mask:0xf
	v_add_f32_dpp v168, v168, v168 quad_perm:[2,3,0,1] row_mask:0xf bank_mask:0xf
	v_add_f32_dpp v169, v169, v169 quad_perm:[2,3,0,1] row_mask:0xf bank_mask:0xf
	v_add_f32_dpp v170, v170, v170 quad_perm:[2,3,0,1] row_mask:0xf bank_mask:0xf
	v_add_f32_dpp v171, v171, v171 quad_perm:[2,3,0,1] row_mask:0xf bank_mask:0xf
	v_add_f32_dpp v172, v172, v172 quad_perm:[2,3,0,1] row_mask:0xf bank_mask:0xf
	v_add_f32_dpp v173, v173, v173 quad_perm:[2,3,0,1] row_mask:0xf bank_mask:0xf
	v_add_f32_dpp v174, v174, v174 quad_perm:[2,3,0,1] row_mask:0xf bank_mask:0xf
	v_add_f32_dpp v175, v175, v175 quad_perm:[2,3,0,1] row_mask:0xf bank_mask:0xf
	v_add_f32_dpp v176, v176, v176 quad_perm:[2,3,0,1] row_mask:0xf bank_mask:0xf
	v_add_f32_dpp v177, v177, v177 quad_perm:[2,3,0,1] row_mask:0xf bank_mask:0xf
	v_add_f32_dpp v178, v178, v178 quad_perm:[2,3,0,1] row_mask:0xf bank_mask:0xf
	v_add_f32_dpp v179, v179, v179 quad_perm:[2,3,0,1] row_mask:0xf bank_mask:0xf
	v_add_f32_dpp v148, v148, v148 row_half_mirror row_mask:0xf bank_mask:0xf
	v_add_f32_dpp v149, v149, v149 row_half_mirror row_mask:0xf bank_mask:0xf
	v_add_f32_dpp v150, v150, v150 row_half_mirror row_mask:0xf bank_mask:0xf
	v_add_f32_dpp v151, v151, v151 row_half_mirror row_mask:0xf bank_mask:0xf
	v_add_f32_dpp v152, v152, v152 row_half_mirror row_mask:0xf bank_mask:0xf
	v_add_f32_dpp v153, v153, v153 row_half_mirror row_mask:0xf bank_mask:0xf
	v_add_f32_dpp v154, v154, v154 row_half_mirror row_mask:0xf bank_mask:0xf
	v_add_f32_dpp v155, v155, v155 row_half_mirror row_mask:0xf bank_mask:0xf
	v_add_f32_dpp v156, v156, v156 row_half_mirror row_mask:0xf bank_mask:0xf
	v_add_f32_dpp v157, v157, v157 row_half_mirror row_mask:0xf bank_mask:0xf
	v_add_f32_dpp v158, v158, v158 row_half_mirror row_mask:0xf bank_mask:0xf
	v_add_f32_dpp v159, v159, v159 row_half_mirror row_mask:0xf bank_mask:0xf
	v_add_f32_dpp v160, v160, v160 row_half_mirror row_mask:0xf bank_mask:0xf
	v_add_f32_dpp v161, v161, v161 row_half_mirror row_mask:0xf bank_mask:0xf
	v_add_f32_dpp v162, v162, v162 row_half_mirror row_mask:0xf bank_mask:0xf
	v_add_f32_dpp v163, v163, v163 row_half_mirror row_mask:0xf bank_mask:0xf
	v_add_f32_dpp v164, v164, v164 row_half_mirror row_mask:0xf bank_mask:0xf
	v_add_f32_dpp v165, v165, v165 row_half_mirror row_mask:0xf bank_mask:0xf
	v_add_f32_dpp v166, v166, v166 row_half_mirror row_mask:0xf bank_mask:0xf
	v_add_f32_dpp v167, v167, v167 row_half_mirror row_mask:0xf bank_mask:0xf
	v_add_f32_dpp v168, v168, v168 row_half_mirror row_mask:0xf bank_mask:0xf
	v_add_f32_dpp v169, v169, v169 row_half_mirror row_mask:0xf bank_mask:0xf
	v_add_f32_dpp v170, v170, v170 row_half_mirror row_mask:0xf bank_mask:0xf
	v_add_f32_dpp v171, v171, v171 row_half_mirror row_mask:0xf bank_mask:0xf
	v_add_f32_dpp v172, v172, v172 row_half_mirror row_mask:0xf bank_mask:0xf
	v_add_f32_dpp v173, v173, v173 row_half_mirror row_mask:0xf bank_mask:0xf
	v_add_f32_dpp v174, v174, v174 row_half_mirror row_mask:0xf bank_mask:0xf
	v_add_f32_dpp v175, v175, v175 row_half_mirror row_mask:0xf bank_mask:0xf
	v_add_f32_dpp v176, v176, v176 row_half_mirror row_mask:0xf bank_mask:0xf
	v_add_f32_dpp v177, v177, v177 row_half_mirror row_mask:0xf bank_mask:0xf
	v_add_f32_dpp v178, v178, v178 row_half_mirror row_mask:0xf bank_mask:0xf
	v_add_f32_dpp v179, v179, v179 row_half_mirror row_mask:0xf bank_mask:0xf
	v_add_f32_dpp v148, v148, v148 row_mirror row_mask:0xf bank_mask:0xf
	v_add_f32_dpp v149, v149, v149 row_mirror row_mask:0xf bank_mask:0xf
	v_add_f32_dpp v150, v150, v150 row_mirror row_mask:0xf bank_mask:0xf
	v_add_f32_dpp v151, v151, v151 row_mirror row_mask:0xf bank_mask:0xf
	v_add_f32_dpp v152, v152, v152 row_mirror row_mask:0xf bank_mask:0xf
	v_add_f32_dpp v153, v153, v153 row_mirror row_mask:0xf bank_mask:0xf
	v_add_f32_dpp v154, v154, v154 row_mirror row_mask:0xf bank_mask:0xf
	v_add_f32_dpp v155, v155, v155 row_mirror row_mask:0xf bank_mask:0xf
	v_add_f32_dpp v156, v156, v156 row_mirror row_mask:0xf bank_mask:0xf
	v_add_f32_dpp v157, v157, v157 row_mirror row_mask:0xf bank_mask:0xf
	v_add_f32_dpp v158, v158, v158 row_mirror row_mask:0xf bank_mask:0xf
	v_add_f32_dpp v159, v159, v159 row_mirror row_mask:0xf bank_mask:0xf
	v_add_f32_dpp v160, v160, v160 row_mirror row_mask:0xf bank_mask:0xf
	v_add_f32_dpp v161, v161, v161 row_mirror row_mask:0xf bank_mask:0xf
	v_add_f32_dpp v162, v162, v162 row_mirror row_mask:0xf bank_mask:0xf
	v_add_f32_dpp v163, v163, v163 row_mirror row_mask:0xf bank_mask:0xf
	v_add_f32_dpp v164, v164, v164 row_mirror row_mask:0xf bank_mask:0xf
	v_add_f32_dpp v165, v165, v165 row_mirror row_mask:0xf bank_mask:0xf
	v_add_f32_dpp v166, v166, v166 row_mirror row_mask:0xf bank_mask:0xf
	v_add_f32_dpp v167, v167, v167 row_mirror row_mask:0xf bank_mask:0xf
	v_add_f32_dpp v168, v168, v168 row_mirror row_mask:0xf bank_mask:0xf
	v_add_f32_dpp v169, v169, v169 row_mirror row_mask:0xf bank_mask:0xf
	v_add_f32_dpp v170, v170, v170 row_mirror row_mask:0xf bank_mask:0xf
	v_add_f32_dpp v171, v171, v171 row_mirror row_mask:0xf bank_mask:0xf
	v_add_f32_dpp v172, v172, v172 row_mirror row_mask:0xf bank_mask:0xf
	v_add_f32_dpp v173, v173, v173 row_mirror row_mask:0xf bank_mask:0xf
	v_add_f32_dpp v174, v174, v174 row_mirror row_mask:0xf bank_mask:0xf
	v_add_f32_dpp v175, v175, v175 row_mirror row_mask:0xf bank_mask:0xf
	v_add_f32_dpp v176, v176, v176 row_mirror row_mask:0xf bank_mask:0xf
	v_add_f32_dpp v177, v177, v177 row_mirror row_mask:0xf bank_mask:0xf
	v_add_f32_dpp v178, v178, v178 row_mirror row_mask:0xf bank_mask:0xf
	v_add_f32_dpp v179, v179, v179 row_mirror row_mask:0xf bank_mask:0xf
	v_fmamk_f32 v148, v148, 0x3a800000, v202
	v_cmp_gt_f32_e32 vcc, s74, v148
	v_mul_f32_e32 v190, 0x4b800000, v148
	s_nop 0
	v_cndmask_b32_e32 v148, v148, v190, vcc
	v_rsq_f32_e32 v148, v148
	s_nop 0
	v_mul_f32_e32 v190, 0x45800000, v148
	v_cndmask_b32_e32 v148, v148, v190, vcc
	v_mul_f32_e32 v98, v98, v148
	v_mul_f32_e32 v99, v99, v148
	v_mul_f32_e32 v100, v100, v148
	v_mul_f32_e32 v101, v101, v148
	v_fma_f32 v98, v180, v98, v184
	v_fma_f32 v99, v181, v99, v185
	v_fma_f32 v100, v182, v100, v186
	v_fma_f32 v101, v183, v101, v187
	v_cvt_pk_bf16_f32 v190, v98, v99
	v_cvt_pk_bf16_f32 v191, v100, v101
	global_store_dwordx2 v188, v[190:191], s[36:37]
	s_add_u32 s36, s36, 0x2000
	s_addc_u32 s37, s37, 0
	v_fmamk_f32 v149, v149, 0x3a800000, v202
	v_cmp_gt_f32_e32 vcc, s74, v149
	v_mul_f32_e32 v190, 0x4b800000, v149
	s_nop 0
	v_cndmask_b32_e32 v149, v149, v190, vcc
	v_rsq_f32_e32 v149, v149
	s_nop 0
	v_mul_f32_e32 v190, 0x45800000, v149
	v_cndmask_b32_e32 v149, v149, v190, vcc
	v_mul_f32_e32 v102, v102, v149
	v_mul_f32_e32 v103, v103, v149
	v_mul_f32_e32 v104, v104, v149
	v_mul_f32_e32 v105, v105, v149
	v_fma_f32 v102, v180, v102, v184
	v_fma_f32 v103, v181, v103, v185
	v_fma_f32 v104, v182, v104, v186
	v_fma_f32 v105, v183, v105, v187
	v_cvt_pk_bf16_f32 v190, v102, v103
	v_cvt_pk_bf16_f32 v191, v104, v105
	global_store_dwordx2 v188, v[190:191], s[36:37]
	s_add_u32 s36, s36, 0x2000
	s_addc_u32 s37, s37, 0
	v_fmamk_f32 v150, v150, 0x3a800000, v202
	v_cmp_gt_f32_e32 vcc, s74, v150
	v_mul_f32_e32 v190, 0x4b800000, v150
	s_nop 0
	v_cndmask_b32_e32 v150, v150, v190, vcc
	v_rsq_f32_e32 v150, v150
	s_nop 0
	v_mul_f32_e32 v190, 0x45800000, v150
	v_cndmask_b32_e32 v150, v150, v190, vcc
	v_mul_f32_e32 v106, v106, v150
	v_mul_f32_e32 v107, v107, v150
	v_mul_f32_e32 v108, v108, v150
	v_mul_f32_e32 v109, v109, v150
	v_fma_f32 v106, v180, v106, v184
	v_fma_f32 v107, v181, v107, v185
	v_fma_f32 v108, v182, v108, v186
	v_fma_f32 v109, v183, v109, v187
	v_cvt_pk_bf16_f32 v190, v106, v107
	v_cvt_pk_bf16_f32 v191, v108, v109
	global_store_dwordx2 v188, v[190:191], s[36:37]
	s_add_u32 s36, s36, 0x2000
	s_addc_u32 s37, s37, 0
	v_fmamk_f32 v151, v151, 0x3a800000, v202
	v_cmp_gt_f32_e32 vcc, s74, v151
	v_mul_f32_e32 v190, 0x4b800000, v151
	s_nop 0
	v_cndmask_b32_e32 v151, v151, v190, vcc
	v_rsq_f32_e32 v151, v151
	s_nop 0
	v_mul_f32_e32 v190, 0x45800000, v151
	v_cndmask_b32_e32 v151, v151, v190, vcc
	v_mul_f32_e32 v110, v110, v151
	v_mul_f32_e32 v111, v111, v151
	v_mul_f32_e32 v112, v112, v151
	v_mul_f32_e32 v113, v113, v151
	v_fma_f32 v110, v180, v110, v184
	v_fma_f32 v111, v181, v111, v185
	v_fma_f32 v112, v182, v112, v186
	v_fma_f32 v113, v183, v113, v187
	v_cvt_pk_bf16_f32 v190, v110, v111
	v_cvt_pk_bf16_f32 v191, v112, v113
	global_store_dwordx2 v188, v[190:191], s[36:37]
	s_add_u32 s36, s36, 0x2000
	s_addc_u32 s37, s37, 0
	v_fmamk_f32 v152, v152, 0x3a800000, v202
	v_cmp_gt_f32_e32 vcc, s74, v152
	v_mul_f32_e32 v190, 0x4b800000, v152
	s_nop 0
	v_cndmask_b32_e32 v152, v152, v190, vcc
	v_rsq_f32_e32 v152, v152
	s_nop 0
	v_mul_f32_e32 v190, 0x45800000, v152
	v_cndmask_b32_e32 v152, v152, v190, vcc
	v_mul_f32_e32 v114, v114, v152
	v_mul_f32_e32 v115, v115, v152
	v_mul_f32_e32 v116, v116, v152
	v_mul_f32_e32 v117, v117, v152
	v_fma_f32 v114, v180, v114, v184
	v_fma_f32 v115, v181, v115, v185
	v_fma_f32 v116, v182, v116, v186
	v_fma_f32 v117, v183, v117, v187
	v_cvt_pk_bf16_f32 v190, v114, v115
	v_cvt_pk_bf16_f32 v191, v116, v117
	global_store_dwordx2 v188, v[190:191], s[36:37]
	s_add_u32 s36, s36, 0x2000
	s_addc_u32 s37, s37, 0
	v_fmamk_f32 v153, v153, 0x3a800000, v202
	v_cmp_gt_f32_e32 vcc, s74, v153
	v_mul_f32_e32 v190, 0x4b800000, v153
	s_nop 0
	v_cndmask_b32_e32 v153, v153, v190, vcc
	v_rsq_f32_e32 v153, v153
	s_nop 0
	v_mul_f32_e32 v190, 0x45800000, v153
	v_cndmask_b32_e32 v153, v153, v190, vcc
	v_mul_f32_e32 v118, v118, v153
	v_mul_f32_e32 v119, v119, v153
	v_mul_f32_e32 v120, v120, v153
	v_mul_f32_e32 v121, v121, v153
	v_fma_f32 v118, v180, v118, v184
	v_fma_f32 v119, v181, v119, v185
	v_fma_f32 v120, v182, v120, v186
	v_fma_f32 v121, v183, v121, v187
	v_cvt_pk_bf16_f32 v190, v118, v119
	v_cvt_pk_bf16_f32 v191, v120, v121
	global_store_dwordx2 v188, v[190:191], s[36:37]
	s_add_u32 s36, s36, 0x2000
	s_addc_u32 s37, s37, 0
	v_fmamk_f32 v154, v154, 0x3a800000, v202
	v_cmp_gt_f32_e32 vcc, s74, v154
	v_mul_f32_e32 v190, 0x4b800000, v154
	s_nop 0
	v_cndmask_b32_e32 v154, v154, v190, vcc
	v_rsq_f32_e32 v154, v154
	s_nop 0
	v_mul_f32_e32 v190, 0x45800000, v154
	v_cndmask_b32_e32 v154, v154, v190, vcc
	v_mul_f32_e32 v122, v122, v154
	v_mul_f32_e32 v123, v123, v154
	v_mul_f32_e32 v124, v124, v154
	v_mul_f32_e32 v125, v125, v154
	v_fma_f32 v122, v180, v122, v184
	v_fma_f32 v123, v181, v123, v185
	v_fma_f32 v124, v182, v124, v186
	v_fma_f32 v125, v183, v125, v187
	v_cvt_pk_bf16_f32 v190, v122, v123
	v_cvt_pk_bf16_f32 v191, v124, v125
	global_store_dwordx2 v188, v[190:191], s[36:37]
	s_add_u32 s36, s36, 0x2000
	s_addc_u32 s37, s37, 0
	v_fmamk_f32 v155, v155, 0x3a800000, v202
	v_cmp_gt_f32_e32 vcc, s74, v155
	v_mul_f32_e32 v190, 0x4b800000, v155
	s_nop 0
	v_cndmask_b32_e32 v155, v155, v190, vcc
	v_rsq_f32_e32 v155, v155
	s_nop 0
	v_mul_f32_e32 v190, 0x45800000, v155
	v_cndmask_b32_e32 v155, v155, v190, vcc
	v_mul_f32_e32 v126, v126, v155
	v_mul_f32_e32 v127, v127, v155
	v_mul_f32_e32 v128, v128, v155
	v_mul_f32_e32 v129, v129, v155
	v_fma_f32 v126, v180, v126, v184
	v_fma_f32 v127, v181, v127, v185
	v_fma_f32 v128, v182, v128, v186
	v_fma_f32 v129, v183, v129, v187
	v_cvt_pk_bf16_f32 v190, v126, v127
	v_cvt_pk_bf16_f32 v191, v128, v129
	global_store_dwordx2 v188, v[190:191], s[36:37]
	s_add_u32 s36, s36, 0x2000
	s_addc_u32 s37, s37, 0
	v_fmamk_f32 v156, v156, 0x3a800000, v202
	v_cmp_gt_f32_e32 vcc, s74, v156
	v_mul_f32_e32 v190, 0x4b800000, v156
	s_nop 0
	v_cndmask_b32_e32 v156, v156, v190, vcc
	v_rsq_f32_e32 v156, v156
	s_nop 0
	v_mul_f32_e32 v190, 0x45800000, v156
	v_cndmask_b32_e32 v156, v156, v190, vcc
	v_mul_f32_e32 v66, v66, v156
	v_mul_f32_e32 v67, v67, v156
	v_mul_f32_e32 v68, v68, v156
	v_mul_f32_e32 v69, v69, v156
	v_fma_f32 v66, v180, v66, v184
	v_fma_f32 v67, v181, v67, v185
	v_fma_f32 v68, v182, v68, v186
	v_fma_f32 v69, v183, v69, v187
	v_cvt_pk_bf16_f32 v190, v66, v67
	v_cvt_pk_bf16_f32 v191, v68, v69
	global_store_dwordx2 v188, v[190:191], s[36:37]
	s_add_u32 s36, s36, 0x2000
	s_addc_u32 s37, s37, 0
	v_fmamk_f32 v157, v157, 0x3a800000, v202
	v_cmp_gt_f32_e32 vcc, s74, v157
	v_mul_f32_e32 v190, 0x4b800000, v157
	s_nop 0
	v_cndmask_b32_e32 v157, v157, v190, vcc
	v_rsq_f32_e32 v157, v157
	s_nop 0
	v_mul_f32_e32 v190, 0x45800000, v157
	v_cndmask_b32_e32 v157, v157, v190, vcc
	v_mul_f32_e32 v70, v70, v157
	v_mul_f32_e32 v71, v71, v157
	v_mul_f32_e32 v72, v72, v157
	v_mul_f32_e32 v73, v73, v157
	v_fma_f32 v70, v180, v70, v184
	v_fma_f32 v71, v181, v71, v185
	v_fma_f32 v72, v182, v72, v186
	v_fma_f32 v73, v183, v73, v187
	v_cvt_pk_bf16_f32 v190, v70, v71
	v_cvt_pk_bf16_f32 v191, v72, v73
	global_store_dwordx2 v188, v[190:191], s[36:37]
	s_add_u32 s36, s36, 0x2000
	s_addc_u32 s37, s37, 0
	v_fmamk_f32 v158, v158, 0x3a800000, v202
	v_cmp_gt_f32_e32 vcc, s74, v158
	v_mul_f32_e32 v190, 0x4b800000, v158
	s_nop 0
	v_cndmask_b32_e32 v158, v158, v190, vcc
	v_rsq_f32_e32 v158, v158
	s_nop 0
	v_mul_f32_e32 v190, 0x45800000, v158
	v_cndmask_b32_e32 v158, v158, v190, vcc
	v_mul_f32_e32 v74, v74, v158
	v_mul_f32_e32 v75, v75, v158
	v_mul_f32_e32 v76, v76, v158
	v_mul_f32_e32 v77, v77, v158
	v_fma_f32 v74, v180, v74, v184
	v_fma_f32 v75, v181, v75, v185
	v_fma_f32 v76, v182, v76, v186
	v_fma_f32 v77, v183, v77, v187
	v_cvt_pk_bf16_f32 v190, v74, v75
	v_cvt_pk_bf16_f32 v191, v76, v77
	global_store_dwordx2 v188, v[190:191], s[36:37]
	s_add_u32 s36, s36, 0x2000
	s_addc_u32 s37, s37, 0
	v_fmamk_f32 v159, v159, 0x3a800000, v202
	v_cmp_gt_f32_e32 vcc, s74, v159
	v_mul_f32_e32 v190, 0x4b800000, v159
	s_nop 0
	v_cndmask_b32_e32 v159, v159, v190, vcc
	v_rsq_f32_e32 v159, v159
	s_nop 0
	v_mul_f32_e32 v190, 0x45800000, v159
	v_cndmask_b32_e32 v159, v159, v190, vcc
	v_mul_f32_e32 v78, v78, v159
	v_mul_f32_e32 v79, v79, v159
	v_mul_f32_e32 v80, v80, v159
	v_mul_f32_e32 v81, v81, v159
	v_fma_f32 v78, v180, v78, v184
	v_fma_f32 v79, v181, v79, v185
	v_fma_f32 v80, v182, v80, v186
	v_fma_f32 v81, v183, v81, v187
	v_cvt_pk_bf16_f32 v190, v78, v79
	v_cvt_pk_bf16_f32 v191, v80, v81
	global_store_dwordx2 v188, v[190:191], s[36:37]
	s_add_u32 s36, s36, 0x2000
	s_addc_u32 s37, s37, 0
	v_fmamk_f32 v160, v160, 0x3a800000, v202
	v_cmp_gt_f32_e32 vcc, s74, v160
	v_mul_f32_e32 v190, 0x4b800000, v160
	s_nop 0
	v_cndmask_b32_e32 v160, v160, v190, vcc
	v_rsq_f32_e32 v160, v160
	s_nop 0
	v_mul_f32_e32 v190, 0x45800000, v160
	v_cndmask_b32_e32 v160, v160, v190, vcc
	v_mul_f32_e32 v82, v82, v160
	v_mul_f32_e32 v83, v83, v160
	v_mul_f32_e32 v84, v84, v160
	v_mul_f32_e32 v85, v85, v160
	v_fma_f32 v82, v180, v82, v184
	v_fma_f32 v83, v181, v83, v185
	v_fma_f32 v84, v182, v84, v186
	v_fma_f32 v85, v183, v85, v187
	v_cvt_pk_bf16_f32 v190, v82, v83
	v_cvt_pk_bf16_f32 v191, v84, v85
	global_store_dwordx2 v188, v[190:191], s[36:37]
	s_add_u32 s36, s36, 0x2000
	s_addc_u32 s37, s37, 0
	v_fmamk_f32 v161, v161, 0x3a800000, v202
	v_cmp_gt_f32_e32 vcc, s74, v161
	v_mul_f32_e32 v190, 0x4b800000, v161
	s_nop 0
	v_cndmask_b32_e32 v161, v161, v190, vcc
	v_rsq_f32_e32 v161, v161
	s_nop 0
	v_mul_f32_e32 v190, 0x45800000, v161
	v_cndmask_b32_e32 v161, v161, v190, vcc
	v_mul_f32_e32 v86, v86, v161
	v_mul_f32_e32 v87, v87, v161
	v_mul_f32_e32 v88, v88, v161
	v_mul_f32_e32 v89, v89, v161
	v_fma_f32 v86, v180, v86, v184
	v_fma_f32 v87, v181, v87, v185
	v_fma_f32 v88, v182, v88, v186
	v_fma_f32 v89, v183, v89, v187
	v_cvt_pk_bf16_f32 v190, v86, v87
	v_cvt_pk_bf16_f32 v191, v88, v89
	global_store_dwordx2 v188, v[190:191], s[36:37]
	s_add_u32 s36, s36, 0x2000
	s_addc_u32 s37, s37, 0
	v_fmamk_f32 v162, v162, 0x3a800000, v202
	v_cmp_gt_f32_e32 vcc, s74, v162
	v_mul_f32_e32 v190, 0x4b800000, v162
	s_nop 0
	v_cndmask_b32_e32 v162, v162, v190, vcc
	v_rsq_f32_e32 v162, v162
	s_nop 0
	v_mul_f32_e32 v190, 0x45800000, v162
	v_cndmask_b32_e32 v162, v162, v190, vcc
	v_mul_f32_e32 v90, v90, v162
	v_mul_f32_e32 v91, v91, v162
	v_mul_f32_e32 v92, v92, v162
	v_mul_f32_e32 v93, v93, v162
	v_fma_f32 v90, v180, v90, v184
	v_fma_f32 v91, v181, v91, v185
	v_fma_f32 v92, v182, v92, v186
	v_fma_f32 v93, v183, v93, v187
	v_cvt_pk_bf16_f32 v190, v90, v91
	v_cvt_pk_bf16_f32 v191, v92, v93
	global_store_dwordx2 v188, v[190:191], s[36:37]
	s_add_u32 s36, s36, 0x2000
	s_addc_u32 s37, s37, 0
	v_fmamk_f32 v163, v163, 0x3a800000, v202
	v_cmp_gt_f32_e32 vcc, s74, v163
	v_mul_f32_e32 v190, 0x4b800000, v163
	s_nop 0
	v_cndmask_b32_e32 v163, v163, v190, vcc
	v_rsq_f32_e32 v163, v163
	s_nop 0
	v_mul_f32_e32 v190, 0x45800000, v163
	v_cndmask_b32_e32 v163, v163, v190, vcc
	v_mul_f32_e32 v94, v94, v163
	v_mul_f32_e32 v95, v95, v163
	v_mul_f32_e32 v96, v96, v163
	v_mul_f32_e32 v97, v97, v163
	v_fma_f32 v94, v180, v94, v184
	v_fma_f32 v95, v181, v95, v185
	v_fma_f32 v96, v182, v96, v186
	v_fma_f32 v97, v183, v97, v187
	v_cvt_pk_bf16_f32 v190, v94, v95
	v_cvt_pk_bf16_f32 v191, v96, v97
	global_store_dwordx2 v188, v[190:191], s[36:37]
	s_add_u32 s36, s36, 0x2000
	s_addc_u32 s37, s37, 0
	v_fmamk_f32 v164, v164, 0x3a800000, v202
	v_cmp_gt_f32_e32 vcc, s74, v164
	v_mul_f32_e32 v190, 0x4b800000, v164
	s_nop 0
	v_cndmask_b32_e32 v164, v164, v190, vcc
	v_rsq_f32_e32 v164, v164
	s_nop 0
	v_mul_f32_e32 v190, 0x45800000, v164
	v_cndmask_b32_e32 v164, v164, v190, vcc
	v_mul_f32_e32 v34, v34, v164
	v_mul_f32_e32 v35, v35, v164
	v_mul_f32_e32 v36, v36, v164
	v_mul_f32_e32 v37, v37, v164
	v_fma_f32 v34, v180, v34, v184
	v_fma_f32 v35, v181, v35, v185
	v_fma_f32 v36, v182, v36, v186
	v_fma_f32 v37, v183, v37, v187
	v_cvt_pk_bf16_f32 v190, v34, v35
	v_cvt_pk_bf16_f32 v191, v36, v37
	global_store_dwordx2 v188, v[190:191], s[36:37]
	s_add_u32 s36, s36, 0x2000
	s_addc_u32 s37, s37, 0
	v_fmamk_f32 v165, v165, 0x3a800000, v202
	v_cmp_gt_f32_e32 vcc, s74, v165
	v_mul_f32_e32 v190, 0x4b800000, v165
	s_nop 0
	v_cndmask_b32_e32 v165, v165, v190, vcc
	v_rsq_f32_e32 v165, v165
	s_nop 0
	v_mul_f32_e32 v190, 0x45800000, v165
	v_cndmask_b32_e32 v165, v165, v190, vcc
	v_mul_f32_e32 v38, v38, v165
	v_mul_f32_e32 v39, v39, v165
	v_mul_f32_e32 v40, v40, v165
	v_mul_f32_e32 v41, v41, v165
	v_fma_f32 v38, v180, v38, v184
	v_fma_f32 v39, v181, v39, v185
	v_fma_f32 v40, v182, v40, v186
	v_fma_f32 v41, v183, v41, v187
	v_cvt_pk_bf16_f32 v190, v38, v39
	v_cvt_pk_bf16_f32 v191, v40, v41
	global_store_dwordx2 v188, v[190:191], s[36:37]
	s_add_u32 s36, s36, 0x2000
	s_addc_u32 s37, s37, 0
	v_fmamk_f32 v166, v166, 0x3a800000, v202
	v_cmp_gt_f32_e32 vcc, s74, v166
	v_mul_f32_e32 v190, 0x4b800000, v166
	s_nop 0
	v_cndmask_b32_e32 v166, v166, v190, vcc
	v_rsq_f32_e32 v166, v166
	s_nop 0
	v_mul_f32_e32 v190, 0x45800000, v166
	v_cndmask_b32_e32 v166, v166, v190, vcc
	v_mul_f32_e32 v42, v42, v166
	v_mul_f32_e32 v43, v43, v166
	v_mul_f32_e32 v44, v44, v166
	v_mul_f32_e32 v45, v45, v166
	v_fma_f32 v42, v180, v42, v184
	v_fma_f32 v43, v181, v43, v185
	v_fma_f32 v44, v182, v44, v186
	v_fma_f32 v45, v183, v45, v187
	v_cvt_pk_bf16_f32 v190, v42, v43
	v_cvt_pk_bf16_f32 v191, v44, v45
	global_store_dwordx2 v188, v[190:191], s[36:37]
	s_add_u32 s36, s36, 0x2000
	s_addc_u32 s37, s37, 0
	v_fmamk_f32 v167, v167, 0x3a800000, v202
	v_cmp_gt_f32_e32 vcc, s74, v167
	v_mul_f32_e32 v190, 0x4b800000, v167
	s_nop 0
	v_cndmask_b32_e32 v167, v167, v190, vcc
	v_rsq_f32_e32 v167, v167
	s_nop 0
	v_mul_f32_e32 v190, 0x45800000, v167
	v_cndmask_b32_e32 v167, v167, v190, vcc
	v_mul_f32_e32 v46, v46, v167
	v_mul_f32_e32 v47, v47, v167
	v_mul_f32_e32 v48, v48, v167
	v_mul_f32_e32 v49, v49, v167
	v_fma_f32 v46, v180, v46, v184
	v_fma_f32 v47, v181, v47, v185
	v_fma_f32 v48, v182, v48, v186
	v_fma_f32 v49, v183, v49, v187
	v_cvt_pk_bf16_f32 v190, v46, v47
	v_cvt_pk_bf16_f32 v191, v48, v49
	global_store_dwordx2 v188, v[190:191], s[36:37]
	s_add_u32 s36, s36, 0x2000
	s_addc_u32 s37, s37, 0
	v_fmamk_f32 v168, v168, 0x3a800000, v202
	v_cmp_gt_f32_e32 vcc, s74, v168
	v_mul_f32_e32 v190, 0x4b800000, v168
	s_nop 0
	v_cndmask_b32_e32 v168, v168, v190, vcc
	v_rsq_f32_e32 v168, v168
	s_nop 0
	v_mul_f32_e32 v190, 0x45800000, v168
	v_cndmask_b32_e32 v168, v168, v190, vcc
	v_mul_f32_e32 v50, v50, v168
	v_mul_f32_e32 v51, v51, v168
	v_mul_f32_e32 v52, v52, v168
	v_mul_f32_e32 v53, v53, v168
	v_fma_f32 v50, v180, v50, v184
	v_fma_f32 v51, v181, v51, v185
	v_fma_f32 v52, v182, v52, v186
	v_fma_f32 v53, v183, v53, v187
	v_cvt_pk_bf16_f32 v190, v50, v51
	v_cvt_pk_bf16_f32 v191, v52, v53
	global_store_dwordx2 v188, v[190:191], s[36:37]
	s_add_u32 s36, s36, 0x2000
	s_addc_u32 s37, s37, 0
	v_fmamk_f32 v169, v169, 0x3a800000, v202
	v_cmp_gt_f32_e32 vcc, s74, v169
	v_mul_f32_e32 v190, 0x4b800000, v169
	s_nop 0
	v_cndmask_b32_e32 v169, v169, v190, vcc
	v_rsq_f32_e32 v169, v169
	s_nop 0
	v_mul_f32_e32 v190, 0x45800000, v169
	v_cndmask_b32_e32 v169, v169, v190, vcc
	v_mul_f32_e32 v54, v54, v169
	v_mul_f32_e32 v55, v55, v169
	v_mul_f32_e32 v56, v56, v169
	v_mul_f32_e32 v57, v57, v169
	v_fma_f32 v54, v180, v54, v184
	v_fma_f32 v55, v181, v55, v185
	v_fma_f32 v56, v182, v56, v186
	v_fma_f32 v57, v183, v57, v187
	v_cvt_pk_bf16_f32 v190, v54, v55
	v_cvt_pk_bf16_f32 v191, v56, v57
	global_store_dwordx2 v188, v[190:191], s[36:37]
	s_add_u32 s36, s36, 0x2000
	s_addc_u32 s37, s37, 0
	v_fmamk_f32 v170, v170, 0x3a800000, v202
	v_cmp_gt_f32_e32 vcc, s74, v170
	v_mul_f32_e32 v190, 0x4b800000, v170
	s_nop 0
	v_cndmask_b32_e32 v170, v170, v190, vcc
	v_rsq_f32_e32 v170, v170
	s_nop 0
	v_mul_f32_e32 v190, 0x45800000, v170
	v_cndmask_b32_e32 v170, v170, v190, vcc
	v_mul_f32_e32 v58, v58, v170
	v_mul_f32_e32 v59, v59, v170
	v_mul_f32_e32 v60, v60, v170
	v_mul_f32_e32 v61, v61, v170
	v_fma_f32 v58, v180, v58, v184
	v_fma_f32 v59, v181, v59, v185
	v_fma_f32 v60, v182, v60, v186
	v_fma_f32 v61, v183, v61, v187
	v_cvt_pk_bf16_f32 v190, v58, v59
	v_cvt_pk_bf16_f32 v191, v60, v61
	global_store_dwordx2 v188, v[190:191], s[36:37]
	s_add_u32 s36, s36, 0x2000
	s_addc_u32 s37, s37, 0
	v_fmamk_f32 v171, v171, 0x3a800000, v202
	v_cmp_gt_f32_e32 vcc, s74, v171
	v_mul_f32_e32 v190, 0x4b800000, v171
	s_nop 0
	v_cndmask_b32_e32 v171, v171, v190, vcc
	v_rsq_f32_e32 v171, v171
	s_nop 0
	v_mul_f32_e32 v190, 0x45800000, v171
	v_cndmask_b32_e32 v171, v171, v190, vcc
	v_mul_f32_e32 v62, v62, v171
	v_mul_f32_e32 v63, v63, v171
	v_mul_f32_e32 v64, v64, v171
	v_mul_f32_e32 v65, v65, v171
	v_fma_f32 v62, v180, v62, v184
	v_fma_f32 v63, v181, v63, v185
	v_fma_f32 v64, v182, v64, v186
	v_fma_f32 v65, v183, v65, v187
	v_cvt_pk_bf16_f32 v190, v62, v63
	v_cvt_pk_bf16_f32 v191, v64, v65
	global_store_dwordx2 v188, v[190:191], s[36:37]
	s_add_u32 s36, s36, 0x2000
	s_addc_u32 s37, s37, 0
	v_fmamk_f32 v172, v172, 0x3a800000, v202
	v_cmp_gt_f32_e32 vcc, s74, v172
	v_mul_f32_e32 v190, 0x4b800000, v172
	s_nop 0
	v_cndmask_b32_e32 v172, v172, v190, vcc
	v_rsq_f32_e32 v172, v172
	s_nop 0
	v_mul_f32_e32 v190, 0x45800000, v172
	v_cndmask_b32_e32 v172, v172, v190, vcc
	v_mul_f32_e32 v132, v132, v172
	v_mul_f32_e32 v133, v133, v172
	v_mul_f32_e32 v134, v134, v172
	v_mul_f32_e32 v135, v135, v172
	v_fma_f32 v132, v180, v132, v184
	v_fma_f32 v133, v181, v133, v185
	v_fma_f32 v134, v182, v134, v186
	v_fma_f32 v135, v183, v135, v187
	v_cvt_pk_bf16_f32 v190, v132, v133
	v_cvt_pk_bf16_f32 v191, v134, v135
	global_store_dwordx2 v188, v[190:191], s[36:37]
	s_add_u32 s36, s36, 0x2000
	s_addc_u32 s37, s37, 0
	v_fmamk_f32 v173, v173, 0x3a800000, v202
	v_cmp_gt_f32_e32 vcc, s74, v173
	v_mul_f32_e32 v190, 0x4b800000, v173
	s_nop 0
	v_cndmask_b32_e32 v173, v173, v190, vcc
	v_rsq_f32_e32 v173, v173
	s_nop 0
	v_mul_f32_e32 v190, 0x45800000, v173
	v_cndmask_b32_e32 v173, v173, v190, vcc
	v_mul_f32_e32 v136, v136, v173
	v_mul_f32_e32 v137, v137, v173
	v_mul_f32_e32 v138, v138, v173
	v_mul_f32_e32 v139, v139, v173
	v_fma_f32 v136, v180, v136, v184
	v_fma_f32 v137, v181, v137, v185
	v_fma_f32 v138, v182, v138, v186
	v_fma_f32 v139, v183, v139, v187
	v_cvt_pk_bf16_f32 v190, v136, v137
	v_cvt_pk_bf16_f32 v191, v138, v139
	global_store_dwordx2 v188, v[190:191], s[36:37]
	s_add_u32 s36, s36, 0x2000
	s_addc_u32 s37, s37, 0
	v_fmamk_f32 v174, v174, 0x3a800000, v202
	v_cmp_gt_f32_e32 vcc, s74, v174
	v_mul_f32_e32 v190, 0x4b800000, v174
	s_nop 0
	v_cndmask_b32_e32 v174, v174, v190, vcc
	v_rsq_f32_e32 v174, v174
	s_nop 0
	v_mul_f32_e32 v190, 0x45800000, v174
	v_cndmask_b32_e32 v174, v174, v190, vcc
	v_mul_f32_e32 v140, v140, v174
	v_mul_f32_e32 v141, v141, v174
	v_mul_f32_e32 v142, v142, v174
	v_mul_f32_e32 v143, v143, v174
	v_fma_f32 v140, v180, v140, v184
	v_fma_f32 v141, v181, v141, v185
	v_fma_f32 v142, v182, v142, v186
	v_fma_f32 v143, v183, v143, v187
	v_cvt_pk_bf16_f32 v190, v140, v141
	v_cvt_pk_bf16_f32 v191, v142, v143
	global_store_dwordx2 v188, v[190:191], s[36:37]
	s_add_u32 s36, s36, 0x2000
	s_addc_u32 s37, s37, 0
	v_fmamk_f32 v175, v175, 0x3a800000, v202
	v_cmp_gt_f32_e32 vcc, s74, v175
	v_mul_f32_e32 v190, 0x4b800000, v175
	s_nop 0
	v_cndmask_b32_e32 v175, v175, v190, vcc
	v_rsq_f32_e32 v175, v175
	s_nop 0
	v_mul_f32_e32 v190, 0x45800000, v175
	v_cndmask_b32_e32 v175, v175, v190, vcc
	v_mul_f32_e32 v144, v144, v175
	v_mul_f32_e32 v145, v145, v175
	v_mul_f32_e32 v146, v146, v175
	v_mul_f32_e32 v147, v147, v175
	v_fma_f32 v144, v180, v144, v184
	v_fma_f32 v145, v181, v145, v185
	v_fma_f32 v146, v182, v146, v186
	v_fma_f32 v147, v183, v147, v187
	v_cvt_pk_bf16_f32 v190, v144, v145
	v_cvt_pk_bf16_f32 v191, v146, v147
	global_store_dwordx2 v188, v[190:191], s[36:37]
	s_add_u32 s36, s36, 0x2000
	s_addc_u32 s37, s37, 0
	v_fmamk_f32 v176, v176, 0x3a800000, v202
	v_cmp_gt_f32_e32 vcc, s74, v176
	v_mul_f32_e32 v190, 0x4b800000, v176
	s_nop 0
	v_cndmask_b32_e32 v176, v176, v190, vcc
	v_rsq_f32_e32 v176, v176
	s_nop 0
	v_mul_f32_e32 v190, 0x45800000, v176
	v_cndmask_b32_e32 v176, v176, v190, vcc
	v_mul_f32_e32 v18, v18, v176
	v_mul_f32_e32 v19, v19, v176
	v_mul_f32_e32 v20, v20, v176
	v_mul_f32_e32 v21, v21, v176
	v_fma_f32 v18, v180, v18, v184
	v_fma_f32 v19, v181, v19, v185
	v_fma_f32 v20, v182, v20, v186
	v_fma_f32 v21, v183, v21, v187
	v_cvt_pk_bf16_f32 v190, v18, v19
	v_cvt_pk_bf16_f32 v191, v20, v21
	global_store_dwordx2 v188, v[190:191], s[36:37]
	s_add_u32 s36, s36, 0x2000
	s_addc_u32 s37, s37, 0
	v_fmamk_f32 v177, v177, 0x3a800000, v202
	v_cmp_gt_f32_e32 vcc, s74, v177
	v_mul_f32_e32 v190, 0x4b800000, v177
	s_nop 0
	v_cndmask_b32_e32 v177, v177, v190, vcc
	v_rsq_f32_e32 v177, v177
	s_nop 0
	v_mul_f32_e32 v190, 0x45800000, v177
	v_cndmask_b32_e32 v177, v177, v190, vcc
	v_mul_f32_e32 v22, v22, v177
	v_mul_f32_e32 v23, v23, v177
	v_mul_f32_e32 v24, v24, v177
	v_mul_f32_e32 v25, v25, v177
	v_fma_f32 v22, v180, v22, v184
	v_fma_f32 v23, v181, v23, v185
	v_fma_f32 v24, v182, v24, v186
	v_fma_f32 v25, v183, v25, v187
	v_cvt_pk_bf16_f32 v190, v22, v23
	v_cvt_pk_bf16_f32 v191, v24, v25
	global_store_dwordx2 v188, v[190:191], s[36:37]
	s_add_u32 s36, s36, 0x2000
	s_addc_u32 s37, s37, 0
	v_fmamk_f32 v178, v178, 0x3a800000, v202
	v_cmp_gt_f32_e32 vcc, s74, v178
	v_mul_f32_e32 v190, 0x4b800000, v178
	s_nop 0
	v_cndmask_b32_e32 v178, v178, v190, vcc
	v_rsq_f32_e32 v178, v178
	s_nop 0
	v_mul_f32_e32 v190, 0x45800000, v178
	v_cndmask_b32_e32 v178, v178, v190, vcc
	v_mul_f32_e32 v26, v26, v178
	v_mul_f32_e32 v27, v27, v178
	v_mul_f32_e32 v28, v28, v178
	v_mul_f32_e32 v29, v29, v178
	v_fma_f32 v26, v180, v26, v184
	v_fma_f32 v27, v181, v27, v185
	v_fma_f32 v28, v182, v28, v186
	v_fma_f32 v29, v183, v29, v187
	v_cvt_pk_bf16_f32 v190, v26, v27
	v_cvt_pk_bf16_f32 v191, v28, v29
	global_store_dwordx2 v188, v[190:191], s[36:37]
	s_add_u32 s36, s36, 0x2000
	s_addc_u32 s37, s37, 0
	v_fmamk_f32 v179, v179, 0x3a800000, v202
	v_cmp_gt_f32_e32 vcc, s74, v179
	v_mul_f32_e32 v190, 0x4b800000, v179
	s_nop 0
	v_cndmask_b32_e32 v179, v179, v190, vcc
	v_rsq_f32_e32 v179, v179
	s_nop 0
	v_mul_f32_e32 v190, 0x45800000, v179
	v_cndmask_b32_e32 v179, v179, v190, vcc
	v_mul_f32_e32 v30, v30, v179
	v_mul_f32_e32 v31, v31, v179
	v_mul_f32_e32 v32, v32, v179
	v_mul_f32_e32 v33, v33, v179
	v_fma_f32 v30, v180, v30, v184
	v_fma_f32 v31, v181, v31, v185
	v_fma_f32 v32, v182, v32, v186
	v_fma_f32 v33, v183, v33, v187
	v_cvt_pk_bf16_f32 v190, v30, v31
	v_cvt_pk_bf16_f32 v191, v32, v33
	global_store_dwordx2 v188, v[190:191], s[36:37]
	s_add_u32 s36, s36, 0x2000
	s_addc_u32 s37, s37, 0
	s_movk_i32 s38, 0x1e00
	s_branch .LBB0_206
.Lmy_norm_plain:
	v_readlane_b32 s0, v242, 6
	s_and_b32 s10, s0, -4
	s_lshl_b32 s0, s96, 10
	s_ashr_i32 s1, s0, 31
	s_mov_b32 s28, 0
	s_lshl_b64 s[0:1], s[0:1], 2
	s_branch .LBB0_200
